# attention probabilities: packed fp32 mul/add split into single ops (packed VOP3P fp32 next to MFMAs stalls issue)
# baseline (speedup 1.0000x reference)
.Latt_unit:
	s_mov_b32 s33, s12
	s_mov_b32 s34, s15
	s_mov_b32 s35, s16
	s_mov_b32 s36, s17
	s_mov_b32 s38, s14
	s_mov_b32 s39, s13
	s_mov_b32 s24, s20
	s_mov_b32 s25, s21
	s_mov_b32 s26, s22
	s_mov_b32 s27, s23
	s_mov_b32 s40, s42
	s_mov_b32 s41, s43
	v_mov_b32_e32 v173, v176
	v_mov_b32_e32 v174, v177
	s_lshr_b32 s44, s33, 0
	s_lshr_b32 s2, s0, 2
	s_lshl_b32 s2, s2, 5
	s_lshr_b32 s3, s15, 2
	s_add_i32 s42, s3, s2
	s_and_b32 s43, s0, 3
	s_waitcnt vmcnt(4)
	ds_write_b128 v253, v[0:3]
	ds_write_b128 v253, v[4:7] offset:1152
	ds_write_b128 v253, v[8:11] offset:2304
	ds_write_b128 v253, v[12:15] offset:3456
	ds_write_b128 v253, v[16:19] offset:4608
	ds_write_b128 v253, v[20:23] offset:5760
	ds_write_b128 v253, v[24:27] offset:55296
	ds_write_b128 v253, v[28:31] offset:56448
	ds_write_b128 v253, v[32:35] offset:57600
	ds_write_b128 v253, v[36:39] offset:58752
	ds_write_b128 v253, v[40:43] offset:59904
	ds_write_b128 v253, v[44:47] offset:61056
	s_lshl_b32 s2, s0, 12
	s_add_i32 s2, s2, 0x1b500
	v_and_b32_e32 v141, 63, v145
	v_lshl_add_u32 v141, v141, 4, s2
	ds_write_b128 v141, v[48:51]
	ds_write_b128 v141, v[52:55] offset:1024
	ds_write_b128 v141, v[56:59] offset:2048
	ds_write_b128 v141, v[60:63] offset:3072
	s_waitcnt lgkmcnt(0)
	s_barrier
	v_add_u32_e32 v134, s42, v160
	v_lshlrev_b32_e32 v134, 2, v134
	v_add_u32_e32 v134, s43, v134
	v_subrev_u32_e32 v135, s15, v134
	v_lshrrev_b32_e32 v136, 4, v135
	v_add_u32_e32 v136, v136, v135
	v_mad_u32_u24 v176, v136, s79, v161
	v_lshl_add_u32 v177, v135, 2, s80
	s_lshl_b32 s2, s43, s13
	s_lshl_b32 s2, s2, 7
	s_add_u32 s86, s20, s2
	s_addc_u32 s87, s21, 0
	s_add_i32 s2, s42, -64
	v_add_u32_e32 v136, s2, v164
	v_ashrrev_i32_e32 v136, 2, v136
	v_med3_i32 v136, v136, 0, s14
	v_lshl_add_u32 v136, v136, 9, v178
	global_load_dwordx4 v[0:3], v136, s[86:87]
	s_add_i32 s2, s42, -56
	v_add_u32_e32 v135, s2, v164
	v_ashrrev_i32_e32 v135, 2, v135
	v_med3_i32 v135, v135, 0, s14
	v_lshl_add_u32 v135, v135, 9, v178
	global_load_dwordx4 v[4:7], v135, s[86:87]
	s_add_i32 s2, s42, -48
	v_add_u32_e32 v136, s2, v164
	v_ashrrev_i32_e32 v136, 2, v136
	v_med3_i32 v136, v136, 0, s14
	v_lshl_add_u32 v136, v136, 9, v178
	global_load_dwordx4 v[8:11], v136, s[86:87]
	s_add_i32 s2, s42, -40
	v_add_u32_e32 v135, s2, v164
	v_ashrrev_i32_e32 v135, 2, v135
	v_med3_i32 v135, v135, 0, s14
	v_lshl_add_u32 v135, v135, 9, v178
	global_load_dwordx4 v[12:15], v135, s[86:87]
	s_add_i32 s2, s42, -32
	v_add_u32_e32 v136, s2, v164
	v_ashrrev_i32_e32 v136, 2, v136
	v_med3_i32 v136, v136, 0, s14
	v_lshl_add_u32 v136, v136, 9, v178
	global_load_dwordx4 v[16:19], v136, s[86:87]
	s_add_i32 s2, s42, -24
	v_add_u32_e32 v135, s2, v164
	v_ashrrev_i32_e32 v135, 2, v135
	v_med3_i32 v135, v135, 0, s14
	v_lshl_add_u32 v135, v135, 9, v178
	global_load_dwordx4 v[20:23], v135, s[86:87]
	s_add_i32 s2, s42, -16
	v_add_u32_e32 v136, s2, v164
	v_ashrrev_i32_e32 v136, 2, v136
	v_med3_i32 v136, v136, 0, s14
	v_lshl_add_u32 v136, v136, 9, v178
	global_load_dwordx4 v[24:27], v136, s[86:87]
	s_add_i32 s2, s42, -8
	v_add_u32_e32 v135, s2, v164
	v_ashrrev_i32_e32 v135, 2, v135
	v_med3_i32 v135, v135, 0, s14
	v_lshl_add_u32 v135, v135, 9, v178
	global_load_dwordx4 v[28:31], v135, s[86:87]
	s_add_i32 s2, s42, 0
	v_add_u32_e32 v136, s2, v164
	v_ashrrev_i32_e32 v136, 2, v136
	v_med3_i32 v136, v136, 0, s14
	v_lshl_add_u32 v136, v136, 9, v178
	global_load_dwordx4 v[32:35], v136, s[86:87]
	s_add_i32 s2, s42, 8
	v_add_u32_e32 v135, s2, v164
	v_ashrrev_i32_e32 v135, 2, v135
	v_med3_i32 v135, v135, 0, s14
	v_lshl_add_u32 v135, v135, 9, v178
	global_load_dwordx4 v[36:39], v135, s[86:87]
	s_add_i32 s2, s42, 16
	v_add_u32_e32 v136, s2, v164
	v_ashrrev_i32_e32 v136, 2, v136
	v_med3_i32 v136, v136, 0, s14
	v_lshl_add_u32 v136, v136, 9, v178
	global_load_dwordx4 v[40:43], v136, s[86:87]
	s_add_i32 s2, s42, 24
	v_add_u32_e32 v135, s2, v164
	v_ashrrev_i32_e32 v135, 2, v135
	v_med3_i32 v135, v135, 0, s14
	v_lshl_add_u32 v135, v135, 9, v178
	global_load_dwordx4 v[44:47], v135, s[86:87]
	s_lshl_b32 s2, s43, s13
	s_lshl_b32 s2, s2, 7
	s_add_u32 s74, s22, s2
	s_addc_u32 s75, s23, 0
	s_add_i32 s2, s42, -64
	v_add_u32_e32 v137, s2, v164
	v_ashrrev_i32_e32 v137, 2, v137
	v_med3_i32 v137, v137, 0, s14
	v_lshl_add_u32 v137, v137, 9, v178
	global_load_dwordx4 v[64:67], v137, s[74:75]
	s_add_i32 s2, s42, -56
	v_add_u32_e32 v137, s2, v164
	v_ashrrev_i32_e32 v137, 2, v137
	v_med3_i32 v137, v137, 0, s14
	v_lshl_add_u32 v137, v137, 9, v178
	global_load_dwordx4 v[68:71], v137, s[74:75]
	s_add_i32 s2, s42, -48
	v_add_u32_e32 v137, s2, v164
	v_ashrrev_i32_e32 v137, 2, v137
	v_med3_i32 v137, v137, 0, s14
	v_lshl_add_u32 v137, v137, 9, v178
	global_load_dwordx4 v[72:75], v137, s[74:75]
	s_add_i32 s2, s42, -40
	v_add_u32_e32 v137, s2, v164
	v_ashrrev_i32_e32 v137, 2, v137
	v_med3_i32 v137, v137, 0, s14
	v_lshl_add_u32 v137, v137, 9, v178
	global_load_dwordx4 v[76:79], v137, s[74:75]
	s_lshl_b32 s2, s43, s13
	s_lshl_b32 s2, s2, 7
	s_add_u32 s74, s22, s2
	s_addc_u32 s75, s23, 0
	s_add_i32 s2, s42, -32
	v_add_u32_e32 v137, s2, v164
	v_ashrrev_i32_e32 v137, 2, v137
	v_med3_i32 v137, v137, 0, s14
	v_lshl_add_u32 v137, v137, 9, v178
	global_load_dwordx4 v[80:83], v137, s[74:75]
	s_add_i32 s2, s42, -24
	v_add_u32_e32 v137, s2, v164
	v_ashrrev_i32_e32 v137, 2, v137
	v_med3_i32 v137, v137, 0, s14
	v_lshl_add_u32 v137, v137, 9, v178
	global_load_dwordx4 v[84:87], v137, s[74:75]
	s_add_i32 s2, s42, -16
	v_add_u32_e32 v137, s2, v164
	v_ashrrev_i32_e32 v137, 2, v137
	v_med3_i32 v137, v137, 0, s14
	v_lshl_add_u32 v137, v137, 9, v178
	global_load_dwordx4 v[88:91], v137, s[74:75]
	s_add_i32 s2, s42, -8
	v_add_u32_e32 v137, s2, v164
	v_ashrrev_i32_e32 v137, 2, v137
	v_med3_i32 v137, v137, 0, s14
	v_lshl_add_u32 v137, v137, 9, v178
	global_load_dwordx4 v[92:95], v137, s[74:75]
	s_lshl_b32 s2, s43, s13
	s_lshl_b32 s2, s2, 7
	s_add_u32 s74, s22, s2
	s_addc_u32 s75, s23, 0
	s_add_i32 s2, s42, 0
	v_add_u32_e32 v137, s2, v164
	v_ashrrev_i32_e32 v137, 2, v137
	v_med3_i32 v137, v137, 0, s14
	v_lshl_add_u32 v137, v137, 9, v178
	global_load_dwordx4 v[96:99], v137, s[74:75]
	s_add_i32 s2, s42, 8
	v_add_u32_e32 v137, s2, v164
	v_ashrrev_i32_e32 v137, 2, v137
	v_med3_i32 v137, v137, 0, s14
	v_lshl_add_u32 v137, v137, 9, v178
	global_load_dwordx4 v[100:103], v137, s[74:75]
	s_add_i32 s2, s42, 16
	v_add_u32_e32 v137, s2, v164
	v_ashrrev_i32_e32 v137, 2, v137
	v_med3_i32 v137, v137, 0, s14
	v_lshl_add_u32 v137, v137, 9, v178
	global_load_dwordx4 v[104:107], v137, s[74:75]
	s_add_i32 s2, s42, 24
	v_add_u32_e32 v137, s2, v164
	v_ashrrev_i32_e32 v137, 2, v137
	v_med3_i32 v137, v137, 0, s14
	v_lshl_add_u32 v137, v137, 9, v178
	global_load_dwordx4 v[108:111], v137, s[74:75]
	v_subrev_u32_e32 v143, s80, v174
	v_lshl_add_u32 v143, v143, 5, v161
	v_add_u32_e32 v143, 0x1b500, v143
	ds_read_b128 v[48:51], v143
	ds_read_b128 v[52:55], v143 offset:64
	ds_read_b128 v[56:59], v143 offset:2048
	ds_read_b128 v[60:63], v143 offset:2112
	s_waitcnt lgkmcnt(0)
	v_mov_b32_e32 v138, 0
	v_mov_b32_e32 v139, 0
	v_mov_b32_e32 v140, 0
	v_mov_b32_e32 v141, 0
	ds_read_b128 v[204:207], v149
	ds_read_b128 v[208:211], v149 offset:64
	ds_read_b128 v[212:215], v149 offset:2304
	ds_read_b128 v[216:219], v149 offset:2368
	ds_read_b128 v[220:223], v149 offset:4608
	ds_read_b128 v[224:227], v149 offset:4672
	ds_read_b128 v[228:231], v149 offset:6912
	ds_read_b128 v[232:235], v149 offset:6976
	s_waitcnt lgkmcnt(0)
	v_mfma_f32_16x16x32_bf16 v[236:239], v[204:207], v[48:51], 0
	v_mfma_f32_16x16x32_bf16 v[236:239], v[208:211], v[52:55], v[236:239]
	v_mfma_f32_16x16x32_bf16 v[240:243], v[212:215], v[48:51], 0
	v_mfma_f32_16x16x32_bf16 v[240:243], v[216:219], v[52:55], v[240:243]
	v_mfma_f32_16x16x32_bf16 v[248:251], v[212:215], v[56:59], 0
	v_mfma_f32_16x16x32_bf16 v[248:251], v[216:219], v[60:63], v[248:251]
	s_nop 7
	s_add_i32 s77, s40, -64
	s_cmp_lt_u32 s77, s44
	s_cselect_b32 s76, s70, s71
	v_min_f32_e32 v152, s76, v236
	v_min_f32_e32 v153, s76, v237
	v_min_f32_e32 v154, s76, v238
	v_min_f32_e32 v155, s76, v239
	v_mfma_f32_16x16x32_bf16 v[236:239], v[220:223], v[48:51], 0
	v_mfma_f32_16x16x32_bf16 v[236:239], v[224:227], v[52:55], v[236:239]
	v_mfma_f32_16x16x32_bf16 v[244:247], v[220:223], v[56:59], 0
	v_mfma_f32_16x16x32_bf16 v[244:247], v[224:227], v[60:63], v[244:247]
	ds_read_b128 v[204:207], v149 offset:9216
	ds_read_b128 v[208:211], v149 offset:9280
	v_mul_f32_e32 v152, s72, v152
	v_mul_f32_e32 v153, s72, v153
	v_mul_f32_e32 v154, s72, v154
	v_mul_f32_e32 v155, s72, v155
	v_exp_f32_e32 v152, v152
	v_exp_f32_e32 v153, v153
	v_exp_f32_e32 v154, v154
	v_exp_f32_e32 v155, v155
	v_cndmask_b32_e64 v152, 0, v152, s[54:55]
	v_cndmask_b32_e64 v153, 0, v153, s[56:57]
	v_cndmask_b32_e64 v154, 0, v154, s[58:59]
	v_cndmask_b32_e64 v155, 0, v155, s[60:61]
	v_add_f32_e32 v138, v138, v152
	v_add_f32_e32 v139, v139, v153
	v_add_f32_e32 v138, v138, v154
	v_add_f32_e32 v139, v139, v155
	v_cvt_pk_bf16_f32 v112, v152, v153
	v_cvt_pk_bf16_f32 v113, v154, v155
	s_add_i32 s77, s40, -48
	s_cmp_lt_u32 s77, s44
	s_cselect_b32 s76, s70, s71
	v_min_f32_e32 v152, s76, v240
	v_min_f32_e32 v153, s76, v241
	v_min_f32_e32 v154, s76, v242
	v_min_f32_e32 v155, s76, v243
	v_min_f32_e32 v156, s76, v248
	v_min_f32_e32 v157, s76, v249
	v_min_f32_e32 v158, s76, v250
	v_min_f32_e32 v159, s76, v251
	v_mfma_f32_16x16x32_bf16 v[240:243], v[228:231], v[48:51], 0
	v_mfma_f32_16x16x32_bf16 v[240:243], v[232:235], v[52:55], v[240:243]
	v_mfma_f32_16x16x32_bf16 v[248:251], v[228:231], v[56:59], 0
	v_mfma_f32_16x16x32_bf16 v[248:251], v[232:235], v[60:63], v[248:251]
	ds_read_b128 v[212:215], v149 offset:11520
	ds_read_b128 v[216:219], v149 offset:11584
	v_mul_f32_e32 v152, s72, v152
	v_mul_f32_e32 v153, s72, v153
	v_mul_f32_e32 v154, s72, v154
	v_mul_f32_e32 v155, s72, v155
	v_exp_f32_e32 v152, v152
	v_exp_f32_e32 v153, v153
	v_exp_f32_e32 v154, v154
	v_exp_f32_e32 v155, v155
	v_add_f32_e32 v138, v138, v152
	v_add_f32_e32 v139, v139, v153
	v_add_f32_e32 v138, v138, v154
	v_add_f32_e32 v139, v139, v155
	v_cvt_pk_bf16_f32 v114, v152, v153
	v_cvt_pk_bf16_f32 v115, v154, v155
	v_mul_f32_e32 v156, s72, v156
	v_mul_f32_e32 v157, s72, v157
	v_mul_f32_e32 v158, s72, v158
	v_mul_f32_e32 v159, s72, v159
	v_exp_f32_e32 v156, v156
	v_exp_f32_e32 v157, v157
	v_exp_f32_e32 v158, v158
	v_exp_f32_e32 v159, v159
	v_cndmask_b32_e64 v156, 0, v156, s[54:55]
	v_cndmask_b32_e64 v157, 0, v157, s[56:57]
	v_cndmask_b32_e64 v158, 0, v158, s[58:59]
	v_cndmask_b32_e64 v159, 0, v159, s[60:61]
	v_add_f32_e32 v140, v140, v156
	v_add_f32_e32 v141, v141, v157
	v_add_f32_e32 v140, v140, v158
	v_add_f32_e32 v141, v141, v159
	v_cvt_pk_bf16_f32 v186, v156, v157
	v_cvt_pk_bf16_f32 v187, v158, v159
	s_add_i32 s77, s40, -32
	s_cmp_lt_u32 s77, s44
	s_cselect_b32 s76, s70, s71
	v_min_f32_e32 v152, s76, v236
	v_min_f32_e32 v153, s76, v237
	v_min_f32_e32 v154, s76, v238
	v_min_f32_e32 v155, s76, v239
	v_min_f32_e32 v156, s76, v244
	v_min_f32_e32 v157, s76, v245
	v_min_f32_e32 v158, s76, v246
	v_min_f32_e32 v159, s76, v247
	s_waitcnt lgkmcnt(2)
	v_mfma_f32_16x16x32_bf16 v[236:239], v[204:207], v[48:51], 0
	v_mfma_f32_16x16x32_bf16 v[236:239], v[208:211], v[52:55], v[236:239]
	v_mfma_f32_16x16x32_bf16 v[244:247], v[204:207], v[56:59], 0
	v_mfma_f32_16x16x32_bf16 v[244:247], v[208:211], v[60:63], v[244:247]
	ds_read_b128 v[220:223], v149 offset:13824
	ds_read_b128 v[224:227], v149 offset:13888
	v_mul_f32_e32 v152, s72, v152
	v_mul_f32_e32 v153, s72, v153
	v_mul_f32_e32 v154, s72, v154
	v_mul_f32_e32 v155, s72, v155
	v_exp_f32_e32 v152, v152
	v_exp_f32_e32 v153, v153
	v_exp_f32_e32 v154, v154
	v_exp_f32_e32 v155, v155
	v_add_f32_e32 v138, v138, v152
	v_add_f32_e32 v139, v139, v153
	v_add_f32_e32 v138, v138, v154
	v_add_f32_e32 v139, v139, v155
	v_cvt_pk_bf16_f32 v116, v152, v153
	v_cvt_pk_bf16_f32 v117, v154, v155
	v_mul_f32_e32 v156, s72, v156
	v_mul_f32_e32 v157, s72, v157
	v_mul_f32_e32 v158, s72, v158
	v_mul_f32_e32 v159, s72, v159
	v_exp_f32_e32 v156, v156
	v_exp_f32_e32 v157, v157
	v_exp_f32_e32 v158, v158
	v_exp_f32_e32 v159, v159
	v_add_f32_e32 v140, v140, v156
	v_add_f32_e32 v141, v141, v157
	v_add_f32_e32 v140, v140, v158
	v_add_f32_e32 v141, v141, v159
	v_cvt_pk_bf16_f32 v188, v156, v157
	v_cvt_pk_bf16_f32 v189, v158, v159
	s_add_i32 s77, s40, -16
	s_cmp_lt_u32 s77, s44
	s_cselect_b32 s76, s70, s71
	v_min_f32_e32 v152, s76, v240
	v_min_f32_e32 v153, s76, v241
	v_min_f32_e32 v154, s76, v242
	v_min_f32_e32 v155, s76, v243
	v_min_f32_e32 v156, s76, v248
	v_min_f32_e32 v157, s76, v249
	v_min_f32_e32 v158, s76, v250
	v_min_f32_e32 v159, s76, v251
	s_waitcnt lgkmcnt(2)
	v_mfma_f32_16x16x32_bf16 v[240:243], v[212:215], v[48:51], 0
	v_mfma_f32_16x16x32_bf16 v[240:243], v[216:219], v[52:55], v[240:243]
	v_mfma_f32_16x16x32_bf16 v[248:251], v[212:215], v[56:59], 0
	v_mfma_f32_16x16x32_bf16 v[248:251], v[216:219], v[60:63], v[248:251]
	ds_read_b128 v[228:231], v149 offset:16128
	ds_read_b128 v[232:235], v149 offset:16192
	v_mul_f32_e32 v152, s72, v152
	v_mul_f32_e32 v153, s72, v153
	v_mul_f32_e32 v154, s72, v154
	v_mul_f32_e32 v155, s72, v155
	v_exp_f32_e32 v152, v152
	v_exp_f32_e32 v153, v153
	v_exp_f32_e32 v154, v154
	v_exp_f32_e32 v155, v155
	v_add_f32_e32 v138, v138, v152
	v_add_f32_e32 v139, v139, v153
	v_add_f32_e32 v138, v138, v154
	v_add_f32_e32 v139, v139, v155
	v_cvt_pk_bf16_f32 v118, v152, v153
	v_cvt_pk_bf16_f32 v119, v154, v155
	v_mul_f32_e32 v156, s72, v156
	v_mul_f32_e32 v157, s72, v157
	v_mul_f32_e32 v158, s72, v158
	v_mul_f32_e32 v159, s72, v159
	v_exp_f32_e32 v156, v156
	v_exp_f32_e32 v157, v157
	v_exp_f32_e32 v158, v158
	v_exp_f32_e32 v159, v159
	v_add_f32_e32 v140, v140, v156
	v_add_f32_e32 v141, v141, v157
	v_add_f32_e32 v140, v140, v158
	v_add_f32_e32 v141, v141, v159
	v_cvt_pk_bf16_f32 v190, v156, v157
	v_cvt_pk_bf16_f32 v191, v158, v159
	s_add_i32 s77, s40, 0
	s_cmp_lt_u32 s77, s44
	s_cselect_b32 s76, s70, s71
	v_min_f32_e32 v152, s76, v236
	v_min_f32_e32 v153, s76, v237
	v_min_f32_e32 v154, s76, v238
	v_min_f32_e32 v155, s76, v239
	v_min_f32_e32 v156, s76, v244
	v_min_f32_e32 v157, s76, v245
	v_min_f32_e32 v158, s76, v246
	v_min_f32_e32 v159, s76, v247
	s_waitcnt lgkmcnt(2)
	v_mfma_f32_16x16x32_bf16 v[236:239], v[220:223], v[48:51], 0
	v_mfma_f32_16x16x32_bf16 v[236:239], v[224:227], v[52:55], v[236:239]
	v_mfma_f32_16x16x32_bf16 v[244:247], v[220:223], v[56:59], 0
	v_mfma_f32_16x16x32_bf16 v[244:247], v[224:227], v[60:63], v[244:247]
	ds_read_b128 v[204:207], v149 offset:18432
	ds_read_b128 v[208:211], v149 offset:18496
	v_mul_f32_e32 v152, s72, v152
	v_mul_f32_e32 v153, s72, v153
	v_mul_f32_e32 v154, s72, v154
	v_mul_f32_e32 v155, s72, v155
	v_exp_f32_e32 v152, v152
	v_exp_f32_e32 v153, v153
	v_exp_f32_e32 v154, v154
	v_exp_f32_e32 v155, v155
	v_add_f32_e32 v138, v138, v152
	v_add_f32_e32 v139, v139, v153
	v_add_f32_e32 v138, v138, v154
	v_add_f32_e32 v139, v139, v155
	v_cvt_pk_bf16_f32 v120, v152, v153
	v_cvt_pk_bf16_f32 v121, v154, v155
	v_mul_f32_e32 v156, s72, v156
	v_mul_f32_e32 v157, s72, v157
	v_mul_f32_e32 v158, s72, v158
	v_mul_f32_e32 v159, s72, v159
	v_exp_f32_e32 v156, v156
	v_exp_f32_e32 v157, v157
	v_exp_f32_e32 v158, v158
	v_exp_f32_e32 v159, v159
	v_add_f32_e32 v140, v140, v156
	v_add_f32_e32 v141, v141, v157
	v_add_f32_e32 v140, v140, v158
	v_add_f32_e32 v141, v141, v159
	v_cvt_pk_bf16_f32 v192, v156, v157
	v_cvt_pk_bf16_f32 v193, v158, v159
	s_add_i32 s77, s40, 16
	s_cmp_lt_u32 s77, s44
	s_cselect_b32 s76, s70, s71
	v_min_f32_e32 v152, s76, v240
	v_min_f32_e32 v153, s76, v241
	v_min_f32_e32 v154, s76, v242
	v_min_f32_e32 v155, s76, v243
	v_min_f32_e32 v156, s76, v248
	v_min_f32_e32 v157, s76, v249
	v_min_f32_e32 v158, s76, v250
	v_min_f32_e32 v159, s76, v251
	s_waitcnt lgkmcnt(2)
	v_mfma_f32_16x16x32_bf16 v[240:243], v[228:231], v[48:51], 0
	v_mfma_f32_16x16x32_bf16 v[240:243], v[232:235], v[52:55], v[240:243]
	v_mfma_f32_16x16x32_bf16 v[248:251], v[228:231], v[56:59], 0
	v_mfma_f32_16x16x32_bf16 v[248:251], v[232:235], v[60:63], v[248:251]
	ds_read_b128 v[212:215], v149 offset:20736
	ds_read_b128 v[216:219], v149 offset:20800
	v_mul_f32_e32 v152, s72, v152
	v_mul_f32_e32 v153, s72, v153
	v_mul_f32_e32 v154, s72, v154
	v_mul_f32_e32 v155, s72, v155
	v_exp_f32_e32 v152, v152
	v_exp_f32_e32 v153, v153
	v_exp_f32_e32 v154, v154
	v_exp_f32_e32 v155, v155
	v_add_f32_e32 v138, v138, v152
	v_add_f32_e32 v139, v139, v153
	v_add_f32_e32 v138, v138, v154
	v_add_f32_e32 v139, v139, v155
	v_cvt_pk_bf16_f32 v122, v152, v153
	v_cvt_pk_bf16_f32 v123, v154, v155
	v_mul_f32_e32 v156, s72, v156
	v_mul_f32_e32 v157, s72, v157
	v_mul_f32_e32 v158, s72, v158
	v_mul_f32_e32 v159, s72, v159
	v_exp_f32_e32 v156, v156
	v_exp_f32_e32 v157, v157
	v_exp_f32_e32 v158, v158
	v_exp_f32_e32 v159, v159
	v_add_f32_e32 v140, v140, v156
	v_add_f32_e32 v141, v141, v157
	v_add_f32_e32 v140, v140, v158
	v_add_f32_e32 v141, v141, v159
	v_cvt_pk_bf16_f32 v194, v156, v157
	v_cvt_pk_bf16_f32 v195, v158, v159
	s_add_i32 s77, s40, 32
	s_cmp_lt_u32 s77, s44
	s_cselect_b32 s76, s70, s71
	v_min_f32_e32 v152, s76, v236
	v_min_f32_e32 v153, s76, v237
	v_min_f32_e32 v154, s76, v238
	v_min_f32_e32 v155, s76, v239
	v_min_f32_e32 v156, s76, v244
	v_min_f32_e32 v157, s76, v245
	v_min_f32_e32 v158, s76, v246
	v_min_f32_e32 v159, s76, v247
	s_waitcnt lgkmcnt(2)
	v_mfma_f32_16x16x32_bf16 v[236:239], v[204:207], v[48:51], 0
	v_mfma_f32_16x16x32_bf16 v[236:239], v[208:211], v[52:55], v[236:239]
	v_mfma_f32_16x16x32_bf16 v[244:247], v[204:207], v[56:59], 0
	v_mfma_f32_16x16x32_bf16 v[244:247], v[208:211], v[60:63], v[244:247]
	v_mul_f32_e32 v152, s72, v152
	v_mul_f32_e32 v153, s72, v153
	v_mul_f32_e32 v154, s72, v154
	v_mul_f32_e32 v155, s72, v155
	v_exp_f32_e32 v152, v152
	v_exp_f32_e32 v153, v153
	v_exp_f32_e32 v154, v154
	v_exp_f32_e32 v155, v155
	v_add_f32_e32 v138, v138, v152
	v_add_f32_e32 v139, v139, v153
	v_add_f32_e32 v138, v138, v154
	v_add_f32_e32 v139, v139, v155
	v_cvt_pk_bf16_f32 v124, v152, v153
	v_cvt_pk_bf16_f32 v125, v154, v155
	v_mul_f32_e32 v156, s72, v156
	v_mul_f32_e32 v157, s72, v157
	v_mul_f32_e32 v158, s72, v158
	v_mul_f32_e32 v159, s72, v159
	v_exp_f32_e32 v156, v156
	v_exp_f32_e32 v157, v157
	v_exp_f32_e32 v158, v158
	v_exp_f32_e32 v159, v159
	v_add_f32_e32 v140, v140, v156
	v_add_f32_e32 v141, v141, v157
	v_add_f32_e32 v140, v140, v158
	v_add_f32_e32 v141, v141, v159
	v_cvt_pk_bf16_f32 v196, v156, v157
	v_cvt_pk_bf16_f32 v197, v158, v159
	s_add_i32 s77, s40, 48
	s_cmp_lt_u32 s77, s44
	s_cselect_b32 s76, s70, s71
	v_min_f32_e32 v152, s76, v240
	v_min_f32_e32 v153, s76, v241
	v_min_f32_e32 v154, s76, v242
	v_min_f32_e32 v155, s76, v243
	v_min_f32_e32 v156, s76, v248
	v_min_f32_e32 v157, s76, v249
	v_min_f32_e32 v158, s76, v250
	v_min_f32_e32 v159, s76, v251
	s_waitcnt lgkmcnt(0)
	v_mfma_f32_16x16x32_bf16 v[248:251], v[212:215], v[56:59], 0
	v_mfma_f32_16x16x32_bf16 v[248:251], v[216:219], v[60:63], v[248:251]
	v_mul_f32_e32 v152, s72, v152
	v_mul_f32_e32 v153, s72, v153
	v_mul_f32_e32 v154, s72, v154
	v_mul_f32_e32 v155, s72, v155
	v_exp_f32_e32 v152, v152
	v_exp_f32_e32 v153, v153
	v_exp_f32_e32 v154, v154
	v_exp_f32_e32 v155, v155
	v_add_f32_e32 v138, v138, v152
	v_add_f32_e32 v139, v139, v153
	v_add_f32_e32 v138, v138, v154
	v_add_f32_e32 v139, v139, v155
	v_cvt_pk_bf16_f32 v126, v152, v153
	v_cvt_pk_bf16_f32 v127, v154, v155
	v_mul_f32_e32 v156, s72, v156
	v_mul_f32_e32 v157, s72, v157
	v_mul_f32_e32 v158, s72, v158
	v_mul_f32_e32 v159, s72, v159
	v_exp_f32_e32 v156, v156
	v_exp_f32_e32 v157, v157
	v_exp_f32_e32 v158, v158
	v_exp_f32_e32 v159, v159
	v_add_f32_e32 v140, v140, v156
	v_add_f32_e32 v141, v141, v157
	v_add_f32_e32 v140, v140, v158
	v_add_f32_e32 v141, v141, v159
	v_cvt_pk_bf16_f32 v198, v156, v157
	v_cvt_pk_bf16_f32 v199, v158, v159
	s_add_i32 s77, s40, 64
	s_cmp_lt_u32 s77, s44
	s_cselect_b32 s76, s70, s71
	v_min_f32_e32 v152, s76, v236
	v_min_f32_e32 v153, s76, v237
	v_min_f32_e32 v154, s76, v238
	v_min_f32_e32 v155, s76, v239
	v_min_f32_e32 v156, s76, v244
	v_min_f32_e32 v157, s76, v245
	v_min_f32_e32 v158, s76, v246
	v_min_f32_e32 v159, s76, v247
	v_mul_f32_e32 v152, s72, v152
	v_mul_f32_e32 v153, s72, v153
	v_mul_f32_e32 v154, s72, v154
	v_mul_f32_e32 v155, s72, v155
	v_exp_f32_e32 v152, v152
	v_exp_f32_e32 v153, v153
	v_exp_f32_e32 v154, v154
	v_exp_f32_e32 v155, v155
	v_cndmask_b32_e64 v152, 0, v152, s[62:63]
	v_cndmask_b32_e64 v153, 0, v153, s[64:65]
	v_cndmask_b32_e64 v154, 0, v154, s[66:67]
	v_cndmask_b32_e64 v155, 0, v155, s[68:69]
	v_add_f32_e32 v138, v138, v152
	v_add_f32_e32 v139, v139, v153
	v_add_f32_e32 v138, v138, v154
	v_add_f32_e32 v139, v139, v155
	v_cvt_pk_bf16_f32 v128, v152, v153
	v_cvt_pk_bf16_f32 v129, v154, v155
	v_mul_f32_e32 v156, s72, v156
	v_mul_f32_e32 v157, s72, v157
	v_mul_f32_e32 v158, s72, v158
	v_mul_f32_e32 v159, s72, v159
	v_exp_f32_e32 v156, v156
	v_exp_f32_e32 v157, v157
	v_exp_f32_e32 v158, v158
	v_exp_f32_e32 v159, v159
	v_add_f32_e32 v140, v140, v156
	v_add_f32_e32 v141, v141, v157
	v_add_f32_e32 v140, v140, v158
	v_add_f32_e32 v141, v141, v159
	v_cvt_pk_bf16_f32 v200, v156, v157
	v_cvt_pk_bf16_f32 v201, v158, v159
	s_add_i32 s77, s40, 80
	s_cmp_lt_u32 s77, s44
	s_cselect_b32 s76, s70, s71
	v_min_f32_e32 v156, s76, v248
	v_min_f32_e32 v157, s76, v249
	v_min_f32_e32 v158, s76, v250
	v_min_f32_e32 v159, s76, v251
	v_mul_f32_e32 v156, s72, v156
	v_mul_f32_e32 v157, s72, v157
	v_mul_f32_e32 v158, s72, v158
	v_mul_f32_e32 v159, s72, v159
	v_exp_f32_e32 v156, v156
	v_exp_f32_e32 v157, v157
	v_exp_f32_e32 v158, v158
	v_exp_f32_e32 v159, v159
	v_cndmask_b32_e64 v156, 0, v156, s[62:63]
	v_cndmask_b32_e64 v157, 0, v157, s[64:65]
	v_cndmask_b32_e64 v158, 0, v158, s[66:67]
	v_cndmask_b32_e64 v159, 0, v159, s[68:69]
	v_add_f32_e32 v140, v140, v156
	v_add_f32_e32 v141, v141, v157
	v_add_f32_e32 v140, v140, v158
	v_add_f32_e32 v141, v141, v159
	v_cvt_pk_bf16_f32 v202, v156, v157
	v_cvt_pk_bf16_f32 v203, v158, v159
	v_add_f32_e32 v132, v138, v139
	v_add_f32_e32 v133, v140, v141
	ds_bpermute_b32 v142, v167, v132
	ds_bpermute_b32 v143, v167, v133
	ds_read_b64_tr_b16 v[236:237], v151 offset:0
	ds_read_b64_tr_b16 v[238:239], v151 offset:2304
	ds_read_b64_tr_b16 v[240:241], v151 offset:32
	ds_read_b64_tr_b16 v[242:243], v151 offset:2336
	ds_read_b64_tr_b16 v[244:245], v151 offset:64
	ds_read_b64_tr_b16 v[246:247], v151 offset:2368
	ds_read_b64_tr_b16 v[248:249], v151 offset:96
	ds_read_b64_tr_b16 v[250:251], v151 offset:2400
	s_waitcnt lgkmcnt(0)
	v_add_f32_e32 v132, v132, v142
	v_add_f32_e32 v133, v133, v143
	ds_bpermute_b32 v142, v168, v132
	ds_bpermute_b32 v143, v168, v133
	ds_read_b64_tr_b16 v[48:49], v151 offset:4608
	ds_read_b64_tr_b16 v[50:51], v151 offset:6912
	ds_read_b64_tr_b16 v[52:53], v151 offset:4640
	ds_read_b64_tr_b16 v[54:55], v151 offset:6944
	ds_read_b64_tr_b16 v[56:57], v151 offset:4672
	ds_read_b64_tr_b16 v[58:59], v151 offset:6976
	ds_read_b64_tr_b16 v[60:61], v151 offset:4704
	ds_read_b64_tr_b16 v[62:63], v151 offset:7008
	v_mfma_f32_16x16x32_bf16 v[204:207], v[236:239], v[112:115], 0
	v_mfma_f32_16x16x32_bf16 v[208:211], v[240:243], v[112:115], 0
	v_mfma_f32_16x16x32_bf16 v[212:215], v[244:247], v[112:115], 0
	v_mfma_f32_16x16x32_bf16 v[216:219], v[248:251], v[112:115], 0
	v_mfma_f32_16x16x32_bf16 v[220:223], v[236:239], v[184:187], 0
	v_mfma_f32_16x16x32_bf16 v[224:227], v[240:243], v[184:187], 0
	v_mfma_f32_16x16x32_bf16 v[228:231], v[244:247], v[184:187], 0
	v_mfma_f32_16x16x32_bf16 v[232:235], v[248:251], v[184:187], 0
	s_waitcnt lgkmcnt(0)
	v_add_f32_e32 v132, v132, v142
	v_add_f32_e32 v133, v133, v143
	ds_read_b64_tr_b16 v[236:237], v151 offset:9216
	ds_read_b64_tr_b16 v[238:239], v151 offset:11520
	ds_read_b64_tr_b16 v[240:241], v151 offset:9248
	ds_read_b64_tr_b16 v[242:243], v151 offset:11552
	ds_read_b64_tr_b16 v[244:245], v151 offset:9280
	ds_read_b64_tr_b16 v[246:247], v151 offset:11584
	ds_read_b64_tr_b16 v[248:249], v151 offset:9312
	ds_read_b64_tr_b16 v[250:251], v151 offset:11616
	v_mfma_f32_16x16x32_bf16 v[204:207], v[48:51], v[116:119], v[204:207]
	v_mfma_f32_16x16x32_bf16 v[208:211], v[52:55], v[116:119], v[208:211]
	v_mfma_f32_16x16x32_bf16 v[212:215], v[56:59], v[116:119], v[212:215]
	v_mfma_f32_16x16x32_bf16 v[216:219], v[60:63], v[116:119], v[216:219]
	v_mfma_f32_16x16x32_bf16 v[220:223], v[48:51], v[188:191], v[220:223]
	v_mfma_f32_16x16x32_bf16 v[224:227], v[52:55], v[188:191], v[224:227]
	v_mfma_f32_16x16x32_bf16 v[228:231], v[56:59], v[188:191], v[228:231]
	v_mfma_f32_16x16x32_bf16 v[232:235], v[60:63], v[188:191], v[232:235]
	s_waitcnt lgkmcnt(0)
	ds_read_b64_tr_b16 v[48:49], v151 offset:13824
	ds_read_b64_tr_b16 v[50:51], v151 offset:16128
	ds_read_b64_tr_b16 v[52:53], v151 offset:13856
	ds_read_b64_tr_b16 v[54:55], v151 offset:16160
	ds_read_b64_tr_b16 v[56:57], v151 offset:13888
	ds_read_b64_tr_b16 v[58:59], v151 offset:16192
	ds_read_b64_tr_b16 v[60:61], v151 offset:13920
	ds_read_b64_tr_b16 v[62:63], v151 offset:16224
	v_mfma_f32_16x16x32_bf16 v[204:207], v[236:239], v[120:123], v[204:207]
	v_mfma_f32_16x16x32_bf16 v[208:211], v[240:243], v[120:123], v[208:211]
	v_mfma_f32_16x16x32_bf16 v[212:215], v[244:247], v[120:123], v[212:215]
	v_mfma_f32_16x16x32_bf16 v[216:219], v[248:251], v[120:123], v[216:219]
	v_mfma_f32_16x16x32_bf16 v[220:223], v[236:239], v[192:195], v[220:223]
	v_mfma_f32_16x16x32_bf16 v[224:227], v[240:243], v[192:195], v[224:227]
	v_mfma_f32_16x16x32_bf16 v[228:231], v[244:247], v[192:195], v[228:231]
	v_mfma_f32_16x16x32_bf16 v[232:235], v[248:251], v[192:195], v[232:235]
	s_waitcnt lgkmcnt(0)
	ds_read_b64_tr_b16 v[236:237], v151 offset:18432
	ds_read_b64_tr_b16 v[238:239], v151 offset:20736
	ds_read_b64_tr_b16 v[240:241], v151 offset:18464
	ds_read_b64_tr_b16 v[242:243], v151 offset:20768
	ds_read_b64_tr_b16 v[244:245], v151 offset:18496
	ds_read_b64_tr_b16 v[246:247], v151 offset:20800
	ds_read_b64_tr_b16 v[248:249], v151 offset:18528
	ds_read_b64_tr_b16 v[250:251], v151 offset:20832
	v_mfma_f32_16x16x32_bf16 v[204:207], v[48:51], v[124:127], v[204:207]
	v_mfma_f32_16x16x32_bf16 v[208:211], v[52:55], v[124:127], v[208:211]
	v_mfma_f32_16x16x32_bf16 v[212:215], v[56:59], v[124:127], v[212:215]
	v_mfma_f32_16x16x32_bf16 v[216:219], v[60:63], v[124:127], v[216:219]
	v_mfma_f32_16x16x32_bf16 v[220:223], v[48:51], v[196:199], v[220:223]
	v_mfma_f32_16x16x32_bf16 v[224:227], v[52:55], v[196:199], v[224:227]
	v_mfma_f32_16x16x32_bf16 v[228:231], v[56:59], v[196:199], v[228:231]
	v_mfma_f32_16x16x32_bf16 v[232:235], v[60:63], v[196:199], v[232:235]
	s_waitcnt lgkmcnt(0)
	v_mfma_f32_16x16x32_bf16 v[204:207], v[236:239], v[128:131], v[204:207]
	v_mfma_f32_16x16x32_bf16 v[208:211], v[240:243], v[128:131], v[208:211]
	v_mfma_f32_16x16x32_bf16 v[212:215], v[244:247], v[128:131], v[212:215]
	v_mfma_f32_16x16x32_bf16 v[216:219], v[248:251], v[128:131], v[216:219]
	v_mfma_f32_16x16x32_bf16 v[220:223], v[236:239], v[200:203], v[220:223]
	v_mfma_f32_16x16x32_bf16 v[224:227], v[240:243], v[200:203], v[224:227]
	v_mfma_f32_16x16x32_bf16 v[228:231], v[244:247], v[200:203], v[228:231]
	v_mfma_f32_16x16x32_bf16 v[232:235], v[248:251], v[200:203], v[232:235]
	s_barrier
	s_add_i32 s2, s42, 32
	v_add_u32_e32 v136, s2, v164
	v_ashrrev_i32_e32 v136, 2, v136
	v_med3_i32 v136, v136, 0, s14
	v_lshl_add_u32 v136, v136, 9, v178
	global_load_dwordx4 v[120:123], v136, s[86:87]
	s_add_i32 s2, s42, 40
	v_add_u32_e32 v135, s2, v164
	v_ashrrev_i32_e32 v135, 2, v135
	v_med3_i32 v135, v135, 0, s14
	v_lshl_add_u32 v135, v135, 9, v178
	global_load_dwordx4 v[124:127], v135, s[86:87]
	s_add_i32 s2, s42, 48
	v_add_u32_e32 v136, s2, v164
	v_ashrrev_i32_e32 v136, 2, v136
	v_med3_i32 v136, v136, 0, s14
	v_lshl_add_u32 v136, v136, 9, v178
	global_load_dwordx4 v[192:195], v136, s[86:87]
	s_add_i32 s2, s42, 56
	v_add_u32_e32 v135, s2, v164
	v_ashrrev_i32_e32 v135, 2, v135
	v_med3_i32 v135, v135, 0, s14
	v_lshl_add_u32 v135, v135, 9, v178
	global_load_dwordx4 v[196:199], v135, s[86:87]
	ds_write_b128 v173, v[204:207] offset:0
	ds_write_b128 v173, v[208:211] offset:64
	ds_write_b128 v173, v[212:215] offset:128
	ds_write_b128 v173, v[216:219] offset:192
	ds_write_b32 v174, v132 offset:0
	ds_write_b128 v173, v[220:223] offset:4624
	ds_write_b128 v173, v[224:227] offset:4688
	ds_write_b128 v173, v[228:231] offset:4752
	ds_write_b128 v173, v[232:235] offset:4816
	ds_write_b32 v174, v133 offset:64
	s_waitcnt lgkmcnt(0)
	s_barrier
	s_mov_b32 s40, s42
	s_mov_b32 s41, s43
	v_mov_b32_e32 v173, v176
	v_mov_b32_e32 v174, v177
	s_lshr_b32 s44, s33, 2
	s_lshr_b32 s42, s15, 4
	s_add_i32 s43, s0, 0
	v_subrev_u32_e32 v143, s80, v174
	v_lshl_add_u32 v143, v143, 5, v161
	v_add_u32_e32 v143, 0x1b500, v143
	ds_read_b128 v[48:51], v143
	ds_read_b128 v[52:55], v143 offset:64
	ds_read_b128 v[56:59], v143 offset:8192
	ds_read_b128 v[60:63], v143 offset:8256
	s_waitcnt lgkmcnt(0)
	v_mov_b32_e32 v138, 0
	v_mov_b32_e32 v139, 0
	v_mov_b32_e32 v140, 0
	v_mov_b32_e32 v141, 0
	s_waitcnt vmcnt(24)
	ds_write_b128 v165, v[0:3]
	ds_write_b128 v165, v[4:7] offset:1152
	ds_write_b128 v165, v[8:11] offset:2304
	ds_write_b128 v165, v[12:15] offset:3456
	s_waitcnt lgkmcnt(0)
	ds_read_b128 v[204:207], v175
	ds_read_b128 v[208:211], v175 offset:64
	ds_read_b128 v[212:215], v175 offset:2304
	ds_read_b128 v[216:219], v175 offset:2368
	s_lshl_b32 s2, s41, s39
	s_lshl_b32 s2, s2, 7
	s_add_u32 s86, s24, s2
	s_addc_u32 s87, s25, 0
	s_add_i32 s2, s40, 64
	v_add_u32_e32 v136, s2, v164
	v_ashrrev_i32_e32 v136, 2, v136
	v_med3_i32 v136, v136, 0, s38
	v_lshl_add_u32 v136, v136, 9, v178
	global_load_dwordx4 v[0:3], v136, s[86:87]
	s_add_i32 s2, s40, 72
	v_add_u32_e32 v135, s2, v164
	v_ashrrev_i32_e32 v135, 2, v135
	v_med3_i32 v135, v135, 0, s38
	v_lshl_add_u32 v135, v135, 9, v178
	global_load_dwordx4 v[4:7], v135, s[86:87]
	s_add_i32 s2, s40, 80
	v_add_u32_e32 v136, s2, v164
	v_ashrrev_i32_e32 v136, 2, v136
	v_med3_i32 v136, v136, 0, s38
	v_lshl_add_u32 v136, v136, 9, v178
	global_load_dwordx4 v[8:11], v136, s[86:87]
	s_add_i32 s2, s40, 88
	v_add_u32_e32 v135, s2, v164
	v_ashrrev_i32_e32 v135, 2, v135
	v_med3_i32 v135, v135, 0, s38
	v_lshl_add_u32 v135, v135, 9, v178
	global_load_dwordx4 v[12:15], v135, s[86:87]
	s_waitcnt vmcnt(24)
	s_waitcnt lgkmcnt(0)
	ds_write_b128 v165, v[16:19]
	ds_write_b128 v165, v[20:23] offset:1152
	ds_write_b128 v165, v[24:27] offset:2304
	ds_write_b128 v165, v[28:31] offset:3456
	v_mfma_f32_16x16x32_bf16 v[236:239], v[204:207], v[48:51], 0
	v_mfma_f32_16x16x32_bf16 v[236:239], v[208:211], v[52:55], v[236:239]
	v_mfma_f32_16x16x32_bf16 v[240:243], v[212:215], v[48:51], 0
	v_mfma_f32_16x16x32_bf16 v[240:243], v[216:219], v[52:55], v[240:243]
	v_mfma_f32_16x16x32_bf16 v[248:251], v[212:215], v[56:59], 0
	v_mfma_f32_16x16x32_bf16 v[248:251], v[216:219], v[60:63], v[248:251]
	s_waitcnt lgkmcnt(0)
	ds_read_b128 v[220:223], v175
	ds_read_b128 v[224:227], v175 offset:64
	s_lshl_b32 s2, s41, s39
	s_lshl_b32 s2, s2, 7
	s_add_u32 s74, s26, s2
	s_addc_u32 s75, s27, 0
	s_add_i32 s2, s40, 32
	v_add_u32_e32 v137, s2, v164
	v_ashrrev_i32_e32 v137, 2, v137
	v_med3_i32 v137, v137, 0, s38
	v_lshl_add_u32 v137, v137, 9, v178
	global_load_dwordx4 v[16:19], v137, s[74:75]
	s_add_i32 s2, s40, 40
	v_add_u32_e32 v137, s2, v164
	v_ashrrev_i32_e32 v137, 2, v137
	v_med3_i32 v137, v137, 0, s38
	v_lshl_add_u32 v137, v137, 9, v178
	global_load_dwordx4 v[20:23], v137, s[74:75]
	s_add_i32 s2, s40, 48
	v_add_u32_e32 v137, s2, v164
	v_ashrrev_i32_e32 v137, 2, v137
	v_med3_i32 v137, v137, 0, s38
	v_lshl_add_u32 v137, v137, 9, v178
	global_load_dwordx4 v[24:27], v137, s[74:75]
	s_add_i32 s2, s40, 56
	v_add_u32_e32 v137, s2, v164
	v_ashrrev_i32_e32 v137, 2, v137
	v_med3_i32 v137, v137, 0, s38
	v_lshl_add_u32 v137, v137, 9, v178
	global_load_dwordx4 v[28:31], v137, s[74:75]
	s_nop 7
	s_add_i32 s77, s40, -64
	s_cmp_lt_u32 s77, s44
	s_cselect_b32 s76, s70, s71
	v_min_f32_e32 v152, s76, v236
	v_min_f32_e32 v153, s76, v237
	v_min_f32_e32 v154, s76, v238
	v_min_f32_e32 v155, s76, v239
	s_waitcnt lgkmcnt(0)
	v_mfma_f32_16x16x32_bf16 v[236:239], v[220:223], v[48:51], 0
	v_mfma_f32_16x16x32_bf16 v[236:239], v[224:227], v[52:55], v[236:239]
	v_mfma_f32_16x16x32_bf16 v[244:247], v[220:223], v[56:59], 0
	v_mfma_f32_16x16x32_bf16 v[244:247], v[224:227], v[60:63], v[244:247]
	s_waitcnt vmcnt(26)
	ds_write_b128 v165, v[32:35]
	ds_write_b128 v165, v[36:39] offset:1152
	ds_read_b128 v[228:231], v175 offset:2304
	ds_read_b128 v[232:235], v175 offset:2368
	v_mul_f32_e32 v152, s72, v152
	v_mul_f32_e32 v153, s72, v153
	v_mul_f32_e32 v154, s72, v154
	v_mul_f32_e32 v155, s72, v155
	v_exp_f32_e32 v152, v152
	v_exp_f32_e32 v153, v153
	v_exp_f32_e32 v154, v154
	v_exp_f32_e32 v155, v155
	v_cndmask_b32_e64 v152, 0, v152, s[54:55]
	v_cndmask_b32_e64 v153, 0, v153, s[56:57]
	v_cndmask_b32_e64 v154, 0, v154, s[58:59]
	v_cndmask_b32_e64 v155, 0, v155, s[60:61]
	v_add_f32_e32 v138, v138, v152
	v_add_f32_e32 v139, v139, v153
	v_add_f32_e32 v138, v138, v154
	v_add_f32_e32 v139, v139, v155
	v_cvt_pk_bf16_f32 v112, v152, v153
	v_cvt_pk_bf16_f32 v113, v154, v155
	s_add_i32 s77, s40, -48
	s_cmp_lt_u32 s77, s44
	s_cselect_b32 s76, s70, s71
	v_min_f32_e32 v152, s76, v240
	v_min_f32_e32 v153, s76, v241
	v_min_f32_e32 v154, s76, v242
	v_min_f32_e32 v155, s76, v243
	v_min_f32_e32 v156, s76, v248
	v_min_f32_e32 v157, s76, v249
	v_min_f32_e32 v158, s76, v250
	v_min_f32_e32 v159, s76, v251
	s_waitcnt lgkmcnt(0)
	v_mfma_f32_16x16x32_bf16 v[240:243], v[228:231], v[48:51], 0
	v_mfma_f32_16x16x32_bf16 v[240:243], v[232:235], v[52:55], v[240:243]
	v_mfma_f32_16x16x32_bf16 v[248:251], v[228:231], v[56:59], 0
	v_mfma_f32_16x16x32_bf16 v[248:251], v[232:235], v[60:63], v[248:251]
	s_waitcnt vmcnt(24)
	ds_write_b128 v165, v[40:43] offset:2304
	ds_write_b128 v165, v[44:47] offset:3456
	ds_read_b128 v[204:207], v175
	ds_read_b128 v[208:211], v175 offset:64
	v_mul_f32_e32 v152, s72, v152
	v_mul_f32_e32 v153, s72, v153
	v_mul_f32_e32 v154, s72, v154
	v_mul_f32_e32 v155, s72, v155
	v_exp_f32_e32 v152, v152
	v_exp_f32_e32 v153, v153
	v_exp_f32_e32 v154, v154
	v_exp_f32_e32 v155, v155
	v_add_f32_e32 v138, v138, v152
	v_add_f32_e32 v139, v139, v153
	v_add_f32_e32 v138, v138, v154
	v_add_f32_e32 v139, v139, v155
	v_cvt_pk_bf16_f32 v114, v152, v153
	v_cvt_pk_bf16_f32 v115, v154, v155
	v_mul_f32_e32 v156, s72, v156
	v_mul_f32_e32 v157, s72, v157
	v_mul_f32_e32 v158, s72, v158
	v_mul_f32_e32 v159, s72, v159
	v_exp_f32_e32 v156, v156
	v_exp_f32_e32 v157, v157
	v_exp_f32_e32 v158, v158
	v_exp_f32_e32 v159, v159
	v_cndmask_b32_e64 v156, 0, v156, s[54:55]
	v_cndmask_b32_e64 v157, 0, v157, s[56:57]
	v_cndmask_b32_e64 v158, 0, v158, s[58:59]
	v_cndmask_b32_e64 v159, 0, v159, s[60:61]
	v_add_f32_e32 v140, v140, v156
	v_add_f32_e32 v141, v141, v157
	v_add_f32_e32 v140, v140, v158
	v_add_f32_e32 v141, v141, v159
	v_cvt_pk_bf16_f32 v186, v156, v157
	v_cvt_pk_bf16_f32 v187, v158, v159
	s_add_i32 s77, s40, -32
	s_cmp_lt_u32 s77, s44
	s_cselect_b32 s76, s70, s71
	v_min_f32_e32 v152, s76, v236
	v_min_f32_e32 v153, s76, v237
	v_min_f32_e32 v154, s76, v238
	v_min_f32_e32 v155, s76, v239
	v_min_f32_e32 v156, s76, v244
	v_min_f32_e32 v157, s76, v245
	v_min_f32_e32 v158, s76, v246
	v_min_f32_e32 v159, s76, v247
	s_waitcnt lgkmcnt(0)
	v_mfma_f32_16x16x32_bf16 v[236:239], v[204:207], v[48:51], 0
	v_mfma_f32_16x16x32_bf16 v[236:239], v[208:211], v[52:55], v[236:239]
	v_mfma_f32_16x16x32_bf16 v[244:247], v[204:207], v[56:59], 0
	v_mfma_f32_16x16x32_bf16 v[244:247], v[208:211], v[60:63], v[244:247]
	s_lshl_b32 s2, s41, s39
	s_lshl_b32 s2, s2, 7
	s_add_u32 s74, s26, s2
	s_addc_u32 s75, s27, 0
	s_add_i32 s2, s40, 64
	v_add_u32_e32 v137, s2, v164
	v_ashrrev_i32_e32 v137, 2, v137
	v_med3_i32 v137, v137, 0, s38
	v_lshl_add_u32 v137, v137, 9, v178
	global_load_dwordx4 v[32:35], v137, s[74:75]
	s_add_i32 s2, s40, 72
	v_add_u32_e32 v137, s2, v164
	v_ashrrev_i32_e32 v137, 2, v137
	v_med3_i32 v137, v137, 0, s38
	v_lshl_add_u32 v137, v137, 9, v178
	global_load_dwordx4 v[36:39], v137, s[74:75]
	s_add_i32 s2, s40, 80
	v_add_u32_e32 v137, s2, v164
	v_ashrrev_i32_e32 v137, 2, v137
	v_med3_i32 v137, v137, 0, s38
	v_lshl_add_u32 v137, v137, 9, v178
	global_load_dwordx4 v[40:43], v137, s[74:75]
	s_add_i32 s2, s40, 88
	v_add_u32_e32 v137, s2, v164
	v_ashrrev_i32_e32 v137, 2, v137
	v_med3_i32 v137, v137, 0, s38
	v_lshl_add_u32 v137, v137, 9, v178
	global_load_dwordx4 v[44:47], v137, s[74:75]
	s_waitcnt vmcnt(14)
	ds_write_b128 v165, v[120:123]
	ds_write_b128 v165, v[124:127] offset:1152
	ds_read_b128 v[212:215], v175 offset:2304
	ds_read_b128 v[216:219], v175 offset:2368
	v_mul_f32_e32 v152, s72, v152
	v_mul_f32_e32 v153, s72, v153
	v_mul_f32_e32 v154, s72, v154
	v_mul_f32_e32 v155, s72, v155
	v_exp_f32_e32 v152, v152
	v_exp_f32_e32 v153, v153
	v_exp_f32_e32 v154, v154
	v_exp_f32_e32 v155, v155
	v_add_f32_e32 v138, v138, v152
	v_add_f32_e32 v139, v139, v153
	v_add_f32_e32 v138, v138, v154
	v_add_f32_e32 v139, v139, v155
	v_cvt_pk_bf16_f32 v116, v152, v153
	v_cvt_pk_bf16_f32 v117, v154, v155
	v_mul_f32_e32 v156, s72, v156
	v_mul_f32_e32 v157, s72, v157
	v_mul_f32_e32 v158, s72, v158
	v_mul_f32_e32 v159, s72, v159
	v_exp_f32_e32 v156, v156
	v_exp_f32_e32 v157, v157
	v_exp_f32_e32 v158, v158
	v_exp_f32_e32 v159, v159
	v_add_f32_e32 v140, v140, v156
	v_add_f32_e32 v141, v141, v157
	v_add_f32_e32 v140, v140, v158
	v_add_f32_e32 v141, v141, v159
	v_cvt_pk_bf16_f32 v188, v156, v157
	v_cvt_pk_bf16_f32 v189, v158, v159
	s_add_i32 s77, s40, -16
	s_cmp_lt_u32 s77, s44
	s_cselect_b32 s76, s70, s71
	v_min_f32_e32 v152, s76, v240
	v_min_f32_e32 v153, s76, v241
	v_min_f32_e32 v154, s76, v242
	v_min_f32_e32 v155, s76, v243
	v_min_f32_e32 v156, s76, v248
	v_min_f32_e32 v157, s76, v249
	v_min_f32_e32 v158, s76, v250
	v_min_f32_e32 v159, s76, v251
	s_waitcnt lgkmcnt(0)
	v_mfma_f32_16x16x32_bf16 v[240:243], v[212:215], v[48:51], 0
	v_mfma_f32_16x16x32_bf16 v[240:243], v[216:219], v[52:55], v[240:243]
	v_mfma_f32_16x16x32_bf16 v[248:251], v[212:215], v[56:59], 0
	v_mfma_f32_16x16x32_bf16 v[248:251], v[216:219], v[60:63], v[248:251]
	s_waitcnt vmcnt(12)
	ds_write_b128 v165, v[192:195] offset:2304
	ds_write_b128 v165, v[196:199] offset:3456
	ds_read_b128 v[220:223], v175
	ds_read_b128 v[224:227], v175 offset:64
	v_mul_f32_e32 v152, s72, v152
	v_mul_f32_e32 v153, s72, v153
	v_mul_f32_e32 v154, s72, v154
	v_mul_f32_e32 v155, s72, v155
	v_exp_f32_e32 v152, v152
	v_exp_f32_e32 v153, v153
	v_exp_f32_e32 v154, v154
	v_exp_f32_e32 v155, v155
	v_add_f32_e32 v138, v138, v152
	v_add_f32_e32 v139, v139, v153
	v_add_f32_e32 v138, v138, v154
	v_add_f32_e32 v139, v139, v155
	v_cvt_pk_bf16_f32 v118, v152, v153
	v_cvt_pk_bf16_f32 v119, v154, v155
	v_mul_f32_e32 v156, s72, v156
	v_mul_f32_e32 v157, s72, v157
	v_mul_f32_e32 v158, s72, v158
	v_mul_f32_e32 v159, s72, v159
	v_exp_f32_e32 v156, v156
	v_exp_f32_e32 v157, v157
	v_exp_f32_e32 v158, v158
	v_exp_f32_e32 v159, v159
	v_add_f32_e32 v140, v140, v156
	v_add_f32_e32 v141, v141, v157
	v_add_f32_e32 v140, v140, v158
	v_add_f32_e32 v141, v141, v159
	v_cvt_pk_bf16_f32 v190, v156, v157
	v_cvt_pk_bf16_f32 v191, v158, v159
	s_add_i32 s77, s40, 0
	s_cmp_lt_u32 s77, s44
	s_cselect_b32 s76, s70, s71
	v_min_f32_e32 v152, s76, v236
	v_min_f32_e32 v153, s76, v237
	v_min_f32_e32 v154, s76, v238
	v_min_f32_e32 v155, s76, v239
	v_min_f32_e32 v156, s76, v244
	v_min_f32_e32 v157, s76, v245
	v_min_f32_e32 v158, s76, v246
	v_min_f32_e32 v159, s76, v247
	s_waitcnt lgkmcnt(0)
	v_mfma_f32_16x16x32_bf16 v[236:239], v[220:223], v[48:51], 0
	v_mfma_f32_16x16x32_bf16 v[236:239], v[224:227], v[52:55], v[236:239]
	v_mfma_f32_16x16x32_bf16 v[244:247], v[220:223], v[56:59], 0
	v_mfma_f32_16x16x32_bf16 v[244:247], v[224:227], v[60:63], v[244:247]
	s_waitcnt vmcnt(10)
	ds_write_b128 v165, v[0:3]
	ds_write_b128 v165, v[4:7] offset:1152
	ds_read_b128 v[228:231], v175 offset:2304
	ds_read_b128 v[232:235], v175 offset:2368
	v_mul_f32_e32 v152, s72, v152
	v_mul_f32_e32 v153, s72, v153
	v_mul_f32_e32 v154, s72, v154
	v_mul_f32_e32 v155, s72, v155
	v_exp_f32_e32 v152, v152
	v_exp_f32_e32 v153, v153
	v_exp_f32_e32 v154, v154
	v_exp_f32_e32 v155, v155
	v_add_f32_e32 v138, v138, v152
	v_add_f32_e32 v139, v139, v153
	v_add_f32_e32 v138, v138, v154
	v_add_f32_e32 v139, v139, v155
	v_cvt_pk_bf16_f32 v120, v152, v153
	v_cvt_pk_bf16_f32 v121, v154, v155
	v_mul_f32_e32 v156, s72, v156
	v_mul_f32_e32 v157, s72, v157
	v_mul_f32_e32 v158, s72, v158
	v_mul_f32_e32 v159, s72, v159
	v_exp_f32_e32 v156, v156
	v_exp_f32_e32 v157, v157
	v_exp_f32_e32 v158, v158
	v_exp_f32_e32 v159, v159
	v_add_f32_e32 v140, v140, v156
	v_add_f32_e32 v141, v141, v157
	v_add_f32_e32 v140, v140, v158
	v_add_f32_e32 v141, v141, v159
	v_cvt_pk_bf16_f32 v192, v156, v157
	v_cvt_pk_bf16_f32 v193, v158, v159
	s_add_i32 s77, s40, 16
	s_cmp_lt_u32 s77, s44
	s_cselect_b32 s76, s70, s71
	v_min_f32_e32 v152, s76, v240
	v_min_f32_e32 v153, s76, v241
	v_min_f32_e32 v154, s76, v242
	v_min_f32_e32 v155, s76, v243
	v_min_f32_e32 v156, s76, v248
	v_min_f32_e32 v157, s76, v249
	v_min_f32_e32 v158, s76, v250
	v_min_f32_e32 v159, s76, v251
	s_waitcnt lgkmcnt(0)
	v_mfma_f32_16x16x32_bf16 v[240:243], v[228:231], v[48:51], 0
	v_mfma_f32_16x16x32_bf16 v[240:243], v[232:235], v[52:55], v[240:243]
	v_mfma_f32_16x16x32_bf16 v[248:251], v[228:231], v[56:59], 0
	v_mfma_f32_16x16x32_bf16 v[248:251], v[232:235], v[60:63], v[248:251]
	s_waitcnt vmcnt(8)
	ds_write_b128 v165, v[8:11] offset:2304
	ds_write_b128 v165, v[12:15] offset:3456
	ds_read_b128 v[204:207], v175
	ds_read_b128 v[208:211], v175 offset:64
	v_mul_f32_e32 v152, s72, v152
	v_mul_f32_e32 v153, s72, v153
	v_mul_f32_e32 v154, s72, v154
	v_mul_f32_e32 v155, s72, v155
	v_exp_f32_e32 v152, v152
	v_exp_f32_e32 v153, v153
	v_exp_f32_e32 v154, v154
	v_exp_f32_e32 v155, v155
	v_add_f32_e32 v138, v138, v152
	v_add_f32_e32 v139, v139, v153
	v_add_f32_e32 v138, v138, v154
	v_add_f32_e32 v139, v139, v155
	v_cvt_pk_bf16_f32 v122, v152, v153
	v_cvt_pk_bf16_f32 v123, v154, v155
	v_mul_f32_e32 v156, s72, v156
	v_mul_f32_e32 v157, s72, v157
	v_mul_f32_e32 v158, s72, v158
	v_mul_f32_e32 v159, s72, v159
	v_exp_f32_e32 v156, v156
	v_exp_f32_e32 v157, v157
	v_exp_f32_e32 v158, v158
	v_exp_f32_e32 v159, v159
	v_add_f32_e32 v140, v140, v156
	v_add_f32_e32 v141, v141, v157
	v_add_f32_e32 v140, v140, v158
	v_add_f32_e32 v141, v141, v159
	v_cvt_pk_bf16_f32 v194, v156, v157
	v_cvt_pk_bf16_f32 v195, v158, v159
	s_add_i32 s77, s40, 32
	s_cmp_lt_u32 s77, s44
	s_cselect_b32 s76, s70, s71
	v_min_f32_e32 v152, s76, v236
	v_min_f32_e32 v153, s76, v237
	v_min_f32_e32 v154, s76, v238
	v_min_f32_e32 v155, s76, v239
	v_min_f32_e32 v156, s76, v244
	v_min_f32_e32 v157, s76, v245
	v_min_f32_e32 v158, s76, v246
	v_min_f32_e32 v159, s76, v247
	s_waitcnt lgkmcnt(0)
	v_mfma_f32_16x16x32_bf16 v[236:239], v[204:207], v[48:51], 0
	v_mfma_f32_16x16x32_bf16 v[236:239], v[208:211], v[52:55], v[236:239]
	v_mfma_f32_16x16x32_bf16 v[244:247], v[204:207], v[56:59], 0
	v_mfma_f32_16x16x32_bf16 v[244:247], v[208:211], v[60:63], v[244:247]
	ds_read_b128 v[212:215], v175 offset:2304
	ds_read_b128 v[216:219], v175 offset:2368
	v_mul_f32_e32 v152, s72, v152
	v_mul_f32_e32 v153, s72, v153
	v_mul_f32_e32 v154, s72, v154
	v_mul_f32_e32 v155, s72, v155
	v_exp_f32_e32 v152, v152
	v_exp_f32_e32 v153, v153
	v_exp_f32_e32 v154, v154
	v_exp_f32_e32 v155, v155
	v_add_f32_e32 v138, v138, v152
	v_add_f32_e32 v139, v139, v153
	v_add_f32_e32 v138, v138, v154
	v_add_f32_e32 v139, v139, v155
	v_cvt_pk_bf16_f32 v124, v152, v153
	v_cvt_pk_bf16_f32 v125, v154, v155
	v_mul_f32_e32 v156, s72, v156
	v_mul_f32_e32 v157, s72, v157
	v_mul_f32_e32 v158, s72, v158
	v_mul_f32_e32 v159, s72, v159
	v_exp_f32_e32 v156, v156
	v_exp_f32_e32 v157, v157
	v_exp_f32_e32 v158, v158
	v_exp_f32_e32 v159, v159
	v_add_f32_e32 v140, v140, v156
	v_add_f32_e32 v141, v141, v157
	v_add_f32_e32 v140, v140, v158
	v_add_f32_e32 v141, v141, v159
	v_cvt_pk_bf16_f32 v196, v156, v157
	v_cvt_pk_bf16_f32 v197, v158, v159
	s_add_i32 s77, s40, 48
	s_cmp_lt_u32 s77, s44
	s_cselect_b32 s76, s70, s71
	v_min_f32_e32 v152, s76, v240
	v_min_f32_e32 v153, s76, v241
	v_min_f32_e32 v154, s76, v242
	v_min_f32_e32 v155, s76, v243
	v_min_f32_e32 v156, s76, v248
	v_min_f32_e32 v157, s76, v249
	v_min_f32_e32 v158, s76, v250
	v_min_f32_e32 v159, s76, v251
	s_waitcnt lgkmcnt(0)
	v_mfma_f32_16x16x32_bf16 v[248:251], v[212:215], v[56:59], 0
	v_mfma_f32_16x16x32_bf16 v[248:251], v[216:219], v[60:63], v[248:251]
	v_mul_f32_e32 v152, s72, v152
	v_mul_f32_e32 v153, s72, v153
	v_mul_f32_e32 v154, s72, v154
	v_mul_f32_e32 v155, s72, v155
	v_exp_f32_e32 v152, v152
	v_exp_f32_e32 v153, v153
	v_exp_f32_e32 v154, v154
	v_exp_f32_e32 v155, v155
	v_add_f32_e32 v138, v138, v152
	v_add_f32_e32 v139, v139, v153
	v_add_f32_e32 v138, v138, v154
	v_add_f32_e32 v139, v139, v155
	v_cvt_pk_bf16_f32 v126, v152, v153
	v_cvt_pk_bf16_f32 v127, v154, v155
	v_mul_f32_e32 v156, s72, v156
	v_mul_f32_e32 v157, s72, v157
	v_mul_f32_e32 v158, s72, v158
	v_mul_f32_e32 v159, s72, v159
	v_exp_f32_e32 v156, v156
	v_exp_f32_e32 v157, v157
	v_exp_f32_e32 v158, v158
	v_exp_f32_e32 v159, v159
	v_add_f32_e32 v140, v140, v156
	v_add_f32_e32 v141, v141, v157
	v_add_f32_e32 v140, v140, v158
	v_add_f32_e32 v141, v141, v159
	v_cvt_pk_bf16_f32 v198, v156, v157
	v_cvt_pk_bf16_f32 v199, v158, v159
	s_add_i32 s77, s40, 64
	s_cmp_lt_u32 s77, s44
	s_cselect_b32 s76, s70, s71
	v_min_f32_e32 v152, s76, v236
	v_min_f32_e32 v153, s76, v237
	v_min_f32_e32 v154, s76, v238
	v_min_f32_e32 v155, s76, v239
	v_min_f32_e32 v156, s76, v244
	v_min_f32_e32 v157, s76, v245
	v_min_f32_e32 v158, s76, v246
	v_min_f32_e32 v159, s76, v247
	v_mul_f32_e32 v152, s72, v152
	v_mul_f32_e32 v153, s72, v153
	v_mul_f32_e32 v154, s72, v154
	v_mul_f32_e32 v155, s72, v155
	v_exp_f32_e32 v152, v152
	v_exp_f32_e32 v153, v153
	v_exp_f32_e32 v154, v154
	v_exp_f32_e32 v155, v155
	v_cndmask_b32_e64 v152, 0, v152, s[62:63]
	v_cndmask_b32_e64 v153, 0, v153, s[64:65]
	v_cndmask_b32_e64 v154, 0, v154, s[66:67]
	v_cndmask_b32_e64 v155, 0, v155, s[68:69]
	v_add_f32_e32 v138, v138, v152
	v_add_f32_e32 v139, v139, v153
	v_add_f32_e32 v138, v138, v154
	v_add_f32_e32 v139, v139, v155
	v_cvt_pk_bf16_f32 v128, v152, v153
	v_cvt_pk_bf16_f32 v129, v154, v155
	v_mul_f32_e32 v156, s72, v156
	v_mul_f32_e32 v157, s72, v157
	v_mul_f32_e32 v158, s72, v158
	v_mul_f32_e32 v159, s72, v159
	v_exp_f32_e32 v156, v156
	v_exp_f32_e32 v157, v157
	v_exp_f32_e32 v158, v158
	v_exp_f32_e32 v159, v159
	v_add_f32_e32 v140, v140, v156
	v_add_f32_e32 v141, v141, v157
	v_add_f32_e32 v140, v140, v158
	v_add_f32_e32 v141, v141, v159
	v_cvt_pk_bf16_f32 v200, v156, v157
	v_cvt_pk_bf16_f32 v201, v158, v159
	s_add_i32 s77, s40, 80
	s_cmp_lt_u32 s77, s44
	s_cselect_b32 s76, s70, s71
	v_min_f32_e32 v156, s76, v248
	v_min_f32_e32 v157, s76, v249
	v_min_f32_e32 v158, s76, v250
	v_min_f32_e32 v159, s76, v251
	v_mul_f32_e32 v156, s72, v156
	v_mul_f32_e32 v157, s72, v157
	v_mul_f32_e32 v158, s72, v158
	v_mul_f32_e32 v159, s72, v159
	v_exp_f32_e32 v156, v156
	v_exp_f32_e32 v157, v157
	v_exp_f32_e32 v158, v158
	v_exp_f32_e32 v159, v159
	v_cndmask_b32_e64 v156, 0, v156, s[62:63]
	v_cndmask_b32_e64 v157, 0, v157, s[64:65]
	v_cndmask_b32_e64 v158, 0, v158, s[66:67]
	v_cndmask_b32_e64 v159, 0, v159, s[68:69]
	v_add_f32_e32 v140, v140, v156
	v_add_f32_e32 v141, v141, v157
	v_add_f32_e32 v140, v140, v158
	v_add_f32_e32 v141, v141, v159
	v_cvt_pk_bf16_f32 v202, v156, v157
	v_cvt_pk_bf16_f32 v203, v158, v159
	v_add_f32_e32 v132, v138, v139
	v_add_f32_e32 v133, v140, v141
	v_add_u32_e32 v134, s42, v160
	v_lshlrev_b32_e32 v134, 4, v134
	v_add_u32_e32 v134, s43, v134
	v_subrev_u32_e32 v135, s15, v134
	v_lshrrev_b32_e32 v136, 4, v135
	v_add_u32_e32 v136, v136, v135
	v_mad_u32_u24 v176, v136, s79, v161
	v_lshl_add_u32 v177, v135, 2, s80
	s_and_b32 s2, s43, 3
	s_lshl_b32 s2, s2, s13
	s_lshr_b32 s3, s43, 2
	s_add_i32 s2, s2, s3
	s_lshl_b32 s2, s2, 7
	s_add_u32 s86, s20, s2
	s_addc_u32 s87, s21, 0
	s_add_i32 s2, s42, -64
	v_add_u32_e32 v136, s2, v164
	v_med3_i32 v136, v136, 0, s14
	v_lshl_add_u32 v136, v136, 9, v162
	global_load_dwordx4 v[0:3], v136, s[86:87]
	s_add_i32 s2, s42, -56
	v_add_u32_e32 v135, s2, v164
	v_med3_i32 v135, v135, 0, s14
	v_lshl_add_u32 v135, v135, 9, v162
	global_load_dwordx4 v[4:7], v135, s[86:87]
	s_add_i32 s2, s42, -48
	v_add_u32_e32 v136, s2, v164
	v_med3_i32 v136, v136, 0, s14
	v_lshl_add_u32 v136, v136, 9, v162
	global_load_dwordx4 v[8:11], v136, s[86:87]
	s_add_i32 s2, s42, -40
	v_add_u32_e32 v135, s2, v164
	v_med3_i32 v135, v135, 0, s14
	v_lshl_add_u32 v135, v135, 9, v162
	global_load_dwordx4 v[12:15], v135, s[86:87]
	ds_bpermute_b32 v142, v167, v132
	ds_bpermute_b32 v143, v167, v133
	ds_write_b128 v165, v[64:67]
	ds_write_b128 v165, v[68:71] offset:1152
	ds_write_b128 v165, v[72:75] offset:2304
	ds_write_b128 v165, v[76:79] offset:3456
	s_waitcnt lgkmcnt(0)
	v_add_f32_e32 v132, v132, v142
	v_add_f32_e32 v133, v133, v143
	ds_bpermute_b32 v142, v168, v132
	ds_bpermute_b32 v143, v168, v133
	ds_read_b64_tr_b16 v[236:237], v166
	ds_read_b64_tr_b16 v[238:239], v166 offset:2304
	ds_read_b64_tr_b16 v[240:241], v166 offset:32
	ds_read_b64_tr_b16 v[242:243], v166 offset:2336
	ds_read_b64_tr_b16 v[244:245], v166 offset:64
	ds_read_b64_tr_b16 v[246:247], v166 offset:2368
	ds_read_b64_tr_b16 v[248:249], v166 offset:96
	ds_read_b64_tr_b16 v[250:251], v166 offset:2400
	s_waitcnt lgkmcnt(0)
	v_add_f32_e32 v132, v132, v142
	v_add_f32_e32 v133, v133, v143
	ds_write_b128 v165, v[80:83]
	ds_write_b128 v165, v[84:87] offset:1152
	ds_write_b128 v165, v[88:91] offset:2304
	ds_write_b128 v165, v[92:95] offset:3456
	v_mfma_f32_16x16x32_bf16 v[204:207], v[236:239], v[112:115], 0
	v_mfma_f32_16x16x32_bf16 v[208:211], v[240:243], v[112:115], 0
	v_mfma_f32_16x16x32_bf16 v[212:215], v[244:247], v[112:115], 0
	v_mfma_f32_16x16x32_bf16 v[216:219], v[248:251], v[112:115], 0
	v_mfma_f32_16x16x32_bf16 v[220:223], v[236:239], v[184:187], 0
	v_mfma_f32_16x16x32_bf16 v[224:227], v[240:243], v[184:187], 0
	v_mfma_f32_16x16x32_bf16 v[228:231], v[244:247], v[184:187], 0
	v_mfma_f32_16x16x32_bf16 v[232:235], v[248:251], v[184:187], 0
	s_waitcnt lgkmcnt(0)
	ds_read_b64_tr_b16 v[236:237], v166
	ds_read_b64_tr_b16 v[238:239], v166 offset:2304
	ds_read_b64_tr_b16 v[240:241], v166 offset:32
	ds_read_b64_tr_b16 v[242:243], v166 offset:2336
	ds_read_b64_tr_b16 v[244:245], v166 offset:64
	ds_read_b64_tr_b16 v[246:247], v166 offset:2368
	ds_read_b64_tr_b16 v[248:249], v166 offset:96
	ds_read_b64_tr_b16 v[250:251], v166 offset:2400
	s_waitcnt lgkmcnt(0)
	ds_write_b128 v165, v[96:99]
	ds_write_b128 v165, v[100:103] offset:1152
	ds_write_b128 v165, v[104:107] offset:2304
	ds_write_b128 v165, v[108:111] offset:3456
	v_mfma_f32_16x16x32_bf16 v[204:207], v[236:239], v[116:119], v[204:207]
	v_mfma_f32_16x16x32_bf16 v[208:211], v[240:243], v[116:119], v[208:211]
	v_mfma_f32_16x16x32_bf16 v[212:215], v[244:247], v[116:119], v[212:215]
	v_mfma_f32_16x16x32_bf16 v[216:219], v[248:251], v[116:119], v[216:219]
	v_mfma_f32_16x16x32_bf16 v[220:223], v[236:239], v[188:191], v[220:223]
	v_mfma_f32_16x16x32_bf16 v[224:227], v[240:243], v[188:191], v[224:227]
	v_mfma_f32_16x16x32_bf16 v[228:231], v[244:247], v[188:191], v[228:231]
	v_mfma_f32_16x16x32_bf16 v[232:235], v[248:251], v[188:191], v[232:235]
	s_waitcnt lgkmcnt(0)
	ds_read_b64_tr_b16 v[236:237], v166
	ds_read_b64_tr_b16 v[238:239], v166 offset:2304
	ds_read_b64_tr_b16 v[240:241], v166 offset:32
	ds_read_b64_tr_b16 v[242:243], v166 offset:2336
	ds_read_b64_tr_b16 v[244:245], v166 offset:64
	ds_read_b64_tr_b16 v[246:247], v166 offset:2368
	ds_read_b64_tr_b16 v[248:249], v166 offset:96
	ds_read_b64_tr_b16 v[250:251], v166 offset:2400
	s_waitcnt lgkmcnt(0)
	s_waitcnt vmcnt(8)
	ds_write_b128 v165, v[16:19]
	ds_write_b128 v165, v[20:23] offset:1152
	ds_write_b128 v165, v[24:27] offset:2304
	ds_write_b128 v165, v[28:31] offset:3456
	v_mfma_f32_16x16x32_bf16 v[204:207], v[236:239], v[120:123], v[204:207]
	v_mfma_f32_16x16x32_bf16 v[208:211], v[240:243], v[120:123], v[208:211]
	v_mfma_f32_16x16x32_bf16 v[212:215], v[244:247], v[120:123], v[212:215]
	v_mfma_f32_16x16x32_bf16 v[216:219], v[248:251], v[120:123], v[216:219]
	v_mfma_f32_16x16x32_bf16 v[220:223], v[236:239], v[192:195], v[220:223]
	v_mfma_f32_16x16x32_bf16 v[224:227], v[240:243], v[192:195], v[224:227]
	v_mfma_f32_16x16x32_bf16 v[228:231], v[244:247], v[192:195], v[228:231]
	v_mfma_f32_16x16x32_bf16 v[232:235], v[248:251], v[192:195], v[232:235]
	s_waitcnt lgkmcnt(0)
	ds_read_b64_tr_b16 v[236:237], v166
	ds_read_b64_tr_b16 v[238:239], v166 offset:2304
	ds_read_b64_tr_b16 v[240:241], v166 offset:32
	ds_read_b64_tr_b16 v[242:243], v166 offset:2336
	ds_read_b64_tr_b16 v[244:245], v166 offset:64
	ds_read_b64_tr_b16 v[246:247], v166 offset:2368
	ds_read_b64_tr_b16 v[248:249], v166 offset:96
	ds_read_b64_tr_b16 v[250:251], v166 offset:2400
	s_waitcnt lgkmcnt(0)
	s_add_i32 s2, s42, -32
	v_add_u32_e32 v136, s2, v164
	v_med3_i32 v136, v136, 0, s14
	v_lshl_add_u32 v136, v136, 9, v162
	global_load_dwordx4 v[16:19], v136, s[86:87]
	s_add_i32 s2, s42, -24
	v_add_u32_e32 v135, s2, v164
	v_med3_i32 v135, v135, 0, s14
	v_lshl_add_u32 v135, v135, 9, v162
	global_load_dwordx4 v[20:23], v135, s[86:87]
	s_add_i32 s2, s42, -16
	v_add_u32_e32 v136, s2, v164
	v_med3_i32 v136, v136, 0, s14
	v_lshl_add_u32 v136, v136, 9, v162
	global_load_dwordx4 v[24:27], v136, s[86:87]
	s_add_i32 s2, s42, -8
	v_add_u32_e32 v135, s2, v164
	v_med3_i32 v135, v135, 0, s14
	v_lshl_add_u32 v135, v135, 9, v162
	global_load_dwordx4 v[28:31], v135, s[86:87]
	s_waitcnt vmcnt(8)
	ds_write_b128 v165, v[32:35]
	ds_write_b128 v165, v[36:39] offset:1152
	ds_write_b128 v165, v[40:43] offset:2304
	ds_write_b128 v165, v[44:47] offset:3456
	v_mfma_f32_16x16x32_bf16 v[204:207], v[236:239], v[124:127], v[204:207]
	v_mfma_f32_16x16x32_bf16 v[208:211], v[240:243], v[124:127], v[208:211]
	v_mfma_f32_16x16x32_bf16 v[212:215], v[244:247], v[124:127], v[212:215]
	v_mfma_f32_16x16x32_bf16 v[216:219], v[248:251], v[124:127], v[216:219]
	v_mfma_f32_16x16x32_bf16 v[220:223], v[236:239], v[196:199], v[220:223]
	v_mfma_f32_16x16x32_bf16 v[224:227], v[240:243], v[196:199], v[224:227]
	v_mfma_f32_16x16x32_bf16 v[228:231], v[244:247], v[196:199], v[228:231]
	v_mfma_f32_16x16x32_bf16 v[232:235], v[248:251], v[196:199], v[232:235]
	s_waitcnt lgkmcnt(0)
	ds_read_b64_tr_b16 v[236:237], v166
	ds_read_b64_tr_b16 v[238:239], v166 offset:2304
	ds_read_b64_tr_b16 v[240:241], v166 offset:32
	ds_read_b64_tr_b16 v[242:243], v166 offset:2336
	ds_read_b64_tr_b16 v[244:245], v166 offset:64
	ds_read_b64_tr_b16 v[246:247], v166 offset:2368
	ds_read_b64_tr_b16 v[248:249], v166 offset:96
	ds_read_b64_tr_b16 v[250:251], v166 offset:2400
	s_waitcnt lgkmcnt(0)
	s_add_i32 s2, s42, 0
	v_add_u32_e32 v136, s2, v164
	v_med3_i32 v136, v136, 0, s14
	v_lshl_add_u32 v136, v136, 9, v162
	global_load_dwordx4 v[32:35], v136, s[86:87]
	s_add_i32 s2, s42, 8
	v_add_u32_e32 v135, s2, v164
	v_med3_i32 v135, v135, 0, s14
	v_lshl_add_u32 v135, v135, 9, v162
	global_load_dwordx4 v[36:39], v135, s[86:87]
	s_add_i32 s2, s42, 16
	v_add_u32_e32 v136, s2, v164
	v_med3_i32 v136, v136, 0, s14
	v_lshl_add_u32 v136, v136, 9, v162
	global_load_dwordx4 v[40:43], v136, s[86:87]
	s_add_i32 s2, s42, 24
	v_add_u32_e32 v135, s2, v164
	v_med3_i32 v135, v135, 0, s14
	v_lshl_add_u32 v135, v135, 9, v162
	global_load_dwordx4 v[44:47], v135, s[86:87]
	v_mfma_f32_16x16x32_bf16 v[204:207], v[236:239], v[128:131], v[204:207]
	v_mfma_f32_16x16x32_bf16 v[208:211], v[240:243], v[128:131], v[208:211]
	v_mfma_f32_16x16x32_bf16 v[212:215], v[244:247], v[128:131], v[212:215]
	v_mfma_f32_16x16x32_bf16 v[216:219], v[248:251], v[128:131], v[216:219]
	v_mfma_f32_16x16x32_bf16 v[220:223], v[236:239], v[200:203], v[220:223]
	v_mfma_f32_16x16x32_bf16 v[224:227], v[240:243], v[200:203], v[224:227]
	v_mfma_f32_16x16x32_bf16 v[228:231], v[244:247], v[200:203], v[228:231]
	v_mfma_f32_16x16x32_bf16 v[232:235], v[248:251], v[200:203], v[232:235]
	s_add_i32 s2, s42, 32
	v_add_u32_e32 v136, s2, v164
	v_med3_i32 v136, v136, 0, s14
	v_lshl_add_u32 v136, v136, 9, v162
	global_load_dwordx4 v[120:123], v136, s[86:87]
	s_add_i32 s2, s42, 40
	v_add_u32_e32 v135, s2, v164
	v_med3_i32 v135, v135, 0, s14
	v_lshl_add_u32 v135, v135, 9, v162
	global_load_dwordx4 v[124:127], v135, s[86:87]
	s_add_i32 s2, s42, 48
	v_add_u32_e32 v136, s2, v164
	v_med3_i32 v136, v136, 0, s14
	v_lshl_add_u32 v136, v136, 9, v162
	global_load_dwordx4 v[192:195], v136, s[86:87]
	s_add_i32 s2, s42, 56
	v_add_u32_e32 v135, s2, v164
	v_med3_i32 v135, v135, 0, s14
	v_lshl_add_u32 v135, v135, 9, v162
	global_load_dwordx4 v[196:199], v135, s[86:87]
	s_and_b32 s2, s43, 3
	s_lshl_b32 s2, s2, s13
	s_lshr_b32 s3, s43, 2
	s_add_i32 s2, s2, s3
	s_lshl_b32 s2, s2, 7
	s_add_u32 s74, s22, s2
	s_addc_u32 s75, s23, 0
	s_add_i32 s2, s42, -64
	v_add_u32_e32 v137, s2, v164
	v_med3_i32 v137, v137, 0, s14
	v_lshl_add_u32 v137, v137, 9, v162
	global_load_dwordx4 v[64:67], v137, s[74:75]
	s_add_i32 s2, s42, -56
	v_add_u32_e32 v137, s2, v164
	v_med3_i32 v137, v137, 0, s14
	v_lshl_add_u32 v137, v137, 9, v162
	global_load_dwordx4 v[68:71], v137, s[74:75]
	s_add_i32 s2, s42, -48
	v_add_u32_e32 v137, s2, v164
	v_med3_i32 v137, v137, 0, s14
	v_lshl_add_u32 v137, v137, 9, v162
	global_load_dwordx4 v[72:75], v137, s[74:75]
	s_add_i32 s2, s42, -40
	v_add_u32_e32 v137, s2, v164
	v_med3_i32 v137, v137, 0, s14
	v_lshl_add_u32 v137, v137, 9, v162
	global_load_dwordx4 v[76:79], v137, s[74:75]
	s_and_b32 s2, s43, 3
	s_lshl_b32 s2, s2, s13
	s_lshr_b32 s3, s43, 2
	s_add_i32 s2, s2, s3
	s_lshl_b32 s2, s2, 7
	s_add_u32 s74, s22, s2
	s_addc_u32 s75, s23, 0
	s_add_i32 s2, s42, -32
	v_add_u32_e32 v137, s2, v164
	v_med3_i32 v137, v137, 0, s14
	v_lshl_add_u32 v137, v137, 9, v162
	global_load_dwordx4 v[80:83], v137, s[74:75]
	s_add_i32 s2, s42, -24
	v_add_u32_e32 v137, s2, v164
	v_med3_i32 v137, v137, 0, s14
	v_lshl_add_u32 v137, v137, 9, v162
	global_load_dwordx4 v[84:87], v137, s[74:75]
	s_add_i32 s2, s42, -16
	v_add_u32_e32 v137, s2, v164
	v_med3_i32 v137, v137, 0, s14
	v_lshl_add_u32 v137, v137, 9, v162
	global_load_dwordx4 v[88:91], v137, s[74:75]
	s_add_i32 s2, s42, -8
	v_add_u32_e32 v137, s2, v164
	v_med3_i32 v137, v137, 0, s14
	v_lshl_add_u32 v137, v137, 9, v162
	global_load_dwordx4 v[92:95], v137, s[74:75]
	s_and_b32 s2, s43, 3
	s_lshl_b32 s2, s2, s13
	s_lshr_b32 s3, s43, 2
	s_add_i32 s2, s2, s3
	s_lshl_b32 s2, s2, 7
	s_add_u32 s74, s22, s2
	s_addc_u32 s75, s23, 0
	s_add_i32 s2, s42, 0
	v_add_u32_e32 v137, s2, v164
	v_med3_i32 v137, v137, 0, s14
	v_lshl_add_u32 v137, v137, 9, v162
	global_load_dwordx4 v[96:99], v137, s[74:75]
	s_add_i32 s2, s42, 8
	v_add_u32_e32 v137, s2, v164
	v_med3_i32 v137, v137, 0, s14
	v_lshl_add_u32 v137, v137, 9, v162
	global_load_dwordx4 v[100:103], v137, s[74:75]
	s_add_i32 s2, s42, 16
	v_add_u32_e32 v137, s2, v164
	v_med3_i32 v137, v137, 0, s14
	v_lshl_add_u32 v137, v137, 9, v162
	global_load_dwordx4 v[104:107], v137, s[74:75]
	s_add_i32 s2, s42, 24
	v_add_u32_e32 v137, s2, v164
	v_med3_i32 v137, v137, 0, s14
	v_lshl_add_u32 v137, v137, 9, v162
	global_load_dwordx4 v[108:111], v137, s[74:75]
	ds_read_b128 v[236:239], v173 offset:0
	ds_read_b128 v[240:243], v173 offset:64
	ds_read_b128 v[244:247], v173 offset:128
	ds_read_b128 v[248:251], v173 offset:192
	ds_read_b32 v142, v174 offset:0
	s_waitcnt lgkmcnt(0)
	v_add_f32_e32 v204, v236, v204
	v_add_f32_e32 v205, v237, v205
	v_add_f32_e32 v206, v238, v206
	v_add_f32_e32 v207, v239, v207
	v_add_f32_e32 v208, v240, v208
	v_add_f32_e32 v209, v241, v209
	v_add_f32_e32 v210, v242, v210
	v_add_f32_e32 v211, v243, v211
	v_add_f32_e32 v212, v244, v212
	v_add_f32_e32 v213, v245, v213
	v_add_f32_e32 v214, v246, v214
	v_add_f32_e32 v215, v247, v215
	v_add_f32_e32 v216, v248, v216
	v_add_f32_e32 v217, v249, v217
	v_add_f32_e32 v218, v250, v218
	v_add_f32_e32 v219, v251, v219
	v_add_f32_e32 v132, v142, v132
	ds_write_b128 v173, v[204:207] offset:0
	ds_write_b128 v173, v[208:211] offset:64
	ds_write_b128 v173, v[212:215] offset:128
	ds_write_b128 v173, v[216:219] offset:192
	ds_write_b32 v174, v132 offset:0
	ds_read_b128 v[236:239], v173 offset:18496
	ds_read_b128 v[240:243], v173 offset:18560
	ds_read_b128 v[244:247], v173 offset:18624
	ds_read_b128 v[248:251], v173 offset:18688
	ds_read_b32 v142, v174 offset:256
	s_waitcnt lgkmcnt(0)
	v_add_f32_e32 v220, v236, v220
	v_add_f32_e32 v221, v237, v221
	v_add_f32_e32 v222, v238, v222
	v_add_f32_e32 v223, v239, v223
	v_add_f32_e32 v224, v240, v224
	v_add_f32_e32 v225, v241, v225
	v_add_f32_e32 v226, v242, v226
	v_add_f32_e32 v227, v243, v227
	v_add_f32_e32 v228, v244, v228
	v_add_f32_e32 v229, v245, v229
	v_add_f32_e32 v230, v246, v230
	v_add_f32_e32 v231, v247, v231
	v_add_f32_e32 v232, v248, v232
	v_add_f32_e32 v233, v249, v233
	v_add_f32_e32 v234, v250, v234
	v_add_f32_e32 v235, v251, v235
	v_add_f32_e32 v133, v142, v133
	ds_write_b128 v173, v[220:223] offset:18496
	ds_write_b128 v173, v[224:227] offset:18560
	ds_write_b128 v173, v[228:231] offset:18624
	ds_write_b128 v173, v[232:235] offset:18688
	ds_write_b32 v174, v133 offset:256
	s_waitcnt lgkmcnt(0)
	s_barrier
	s_mov_b32 s40, s42
	s_mov_b32 s41, s43
	v_mov_b32_e32 v173, v176
	v_mov_b32_e32 v174, v177
	s_lshr_b32 s44, s33, 4
	s_lshr_b32 s42, s15, 4
	s_add_i32 s43, s0, 8
	v_subrev_u32_e32 v143, s80, v174
	v_lshl_add_u32 v143, v143, 5, v161
	v_add_u32_e32 v143, 0x1b500, v143
	ds_read_b128 v[48:51], v143
	ds_read_b128 v[52:55], v143 offset:64
	s_waitcnt lgkmcnt(0)
	v_mov_b32_e32 v138, 0
	v_mov_b32_e32 v139, 0
	s_waitcnt vmcnt(24)
	ds_write_b128 v165, v[0:3]
	ds_write_b128 v165, v[4:7] offset:1152
	ds_write_b128 v165, v[8:11] offset:2304
	ds_write_b128 v165, v[12:15] offset:3456
	s_waitcnt lgkmcnt(0)
	ds_read_b128 v[204:207], v175
	ds_read_b128 v[208:211], v175 offset:64
	ds_read_b128 v[212:215], v175 offset:2304
	ds_read_b128 v[216:219], v175 offset:2368
	s_and_b32 s2, s41, 3
	s_lshl_b32 s2, s2, s39
	s_lshr_b32 s3, s41, 2
	s_add_i32 s2, s2, s3
	s_lshl_b32 s2, s2, 7
	s_add_u32 s86, s24, s2
	s_addc_u32 s87, s25, 0
	s_add_i32 s2, s40, 64
	v_add_u32_e32 v136, s2, v164
	v_med3_i32 v136, v136, 0, s38
	v_lshl_add_u32 v136, v136, 9, v162
	global_load_dwordx4 v[0:3], v136, s[86:87]
	s_add_i32 s2, s40, 72
	v_add_u32_e32 v135, s2, v164
	v_med3_i32 v135, v135, 0, s38
	v_lshl_add_u32 v135, v135, 9, v162
	global_load_dwordx4 v[4:7], v135, s[86:87]
	s_waitcnt vmcnt(22)
	s_waitcnt lgkmcnt(0)
	ds_write_b128 v165, v[16:19]
	ds_write_b128 v165, v[20:23] offset:1152
	ds_write_b128 v165, v[24:27] offset:2304
	ds_write_b128 v165, v[28:31] offset:3456
	v_mfma_f32_16x16x32_bf16 v[236:239], v[204:207], v[48:51], 0
	v_mfma_f32_16x16x32_bf16 v[236:239], v[208:211], v[52:55], v[236:239]
	v_mfma_f32_16x16x32_bf16 v[240:243], v[212:215], v[48:51], 0
	v_mfma_f32_16x16x32_bf16 v[240:243], v[216:219], v[52:55], v[240:243]
	s_waitcnt lgkmcnt(0)
	ds_read_b128 v[220:223], v175
	ds_read_b128 v[224:227], v175 offset:64
	s_and_b32 s2, s41, 3
	s_lshl_b32 s2, s2, s39
	s_lshr_b32 s3, s41, 2
	s_add_i32 s2, s2, s3
	s_lshl_b32 s2, s2, 7
	s_add_u32 s74, s26, s2
	s_addc_u32 s75, s27, 0
	s_add_i32 s2, s40, 32
	v_add_u32_e32 v137, s2, v164
	v_med3_i32 v137, v137, 0, s38
	v_lshl_add_u32 v137, v137, 9, v162
	global_load_dwordx4 v[16:19], v137, s[74:75]
	s_add_i32 s2, s40, 40
	v_add_u32_e32 v137, s2, v164
	v_med3_i32 v137, v137, 0, s38
	v_lshl_add_u32 v137, v137, 9, v162
	global_load_dwordx4 v[20:23], v137, s[74:75]
	s_add_i32 s2, s40, 48
	v_add_u32_e32 v137, s2, v164
	v_med3_i32 v137, v137, 0, s38
	v_lshl_add_u32 v137, v137, 9, v162
	global_load_dwordx4 v[24:27], v137, s[74:75]
	s_add_i32 s2, s40, 56
	v_add_u32_e32 v137, s2, v164
	v_med3_i32 v137, v137, 0, s38
	v_lshl_add_u32 v137, v137, 9, v162
	global_load_dwordx4 v[28:31], v137, s[74:75]
	s_nop 7
	s_add_i32 s77, s40, -64
	s_cmp_lt_u32 s77, s44
	s_cselect_b32 s76, s70, s71
	v_min_f32_e32 v152, s76, v236
	v_min_f32_e32 v153, s76, v237
	v_min_f32_e32 v154, s76, v238
	v_min_f32_e32 v155, s76, v239
	s_waitcnt lgkmcnt(0)
	v_mfma_f32_16x16x32_bf16 v[236:239], v[220:223], v[48:51], 0
	v_mfma_f32_16x16x32_bf16 v[236:239], v[224:227], v[52:55], v[236:239]
	s_waitcnt vmcnt(24)
	ds_write_b128 v165, v[32:35]
	ds_write_b128 v165, v[36:39] offset:1152
	ds_read_b128 v[228:231], v175 offset:2304
	ds_read_b128 v[232:235], v175 offset:2368
	v_mul_f32_e32 v152, s72, v152
	v_mul_f32_e32 v153, s72, v153
	v_mul_f32_e32 v154, s72, v154
	v_mul_f32_e32 v155, s72, v155
	v_exp_f32_e32 v152, v152
	v_exp_f32_e32 v153, v153
	v_exp_f32_e32 v154, v154
	v_exp_f32_e32 v155, v155
	v_cndmask_b32_e64 v152, 0, v152, s[54:55]
	v_cndmask_b32_e64 v153, 0, v153, s[56:57]
	v_cndmask_b32_e64 v154, 0, v154, s[58:59]
	v_cndmask_b32_e64 v155, 0, v155, s[60:61]
	v_add_f32_e32 v138, v138, v152
	v_add_f32_e32 v139, v139, v153
	v_add_f32_e32 v138, v138, v154
	v_add_f32_e32 v139, v139, v155
	v_cvt_pk_bf16_f32 v112, v152, v153
	v_cvt_pk_bf16_f32 v113, v154, v155
	s_add_i32 s77, s40, -48
	s_cmp_lt_u32 s77, s44
	s_cselect_b32 s76, s70, s71
	v_min_f32_e32 v152, s76, v240
	v_min_f32_e32 v153, s76, v241
	v_min_f32_e32 v154, s76, v242
	v_min_f32_e32 v155, s76, v243
	s_waitcnt lgkmcnt(0)
	v_mfma_f32_16x16x32_bf16 v[240:243], v[228:231], v[48:51], 0
	v_mfma_f32_16x16x32_bf16 v[240:243], v[232:235], v[52:55], v[240:243]
	s_waitcnt vmcnt(22)
	ds_write_b128 v165, v[40:43] offset:2304
	ds_write_b128 v165, v[44:47] offset:3456
	ds_read_b128 v[204:207], v175
	ds_read_b128 v[208:211], v175 offset:64
	v_mul_f32_e32 v152, s72, v152
	v_mul_f32_e32 v153, s72, v153
	v_mul_f32_e32 v154, s72, v154
	v_mul_f32_e32 v155, s72, v155
	v_exp_f32_e32 v152, v152
	v_exp_f32_e32 v153, v153
	v_exp_f32_e32 v154, v154
	v_exp_f32_e32 v155, v155
	v_add_f32_e32 v138, v138, v152
	v_add_f32_e32 v139, v139, v153
	v_add_f32_e32 v138, v138, v154
	v_add_f32_e32 v139, v139, v155
	v_cvt_pk_bf16_f32 v114, v152, v153
	v_cvt_pk_bf16_f32 v115, v154, v155
	s_add_i32 s77, s40, -32
	s_cmp_lt_u32 s77, s44
	s_cselect_b32 s76, s70, s71
	v_min_f32_e32 v152, s76, v236
	v_min_f32_e32 v153, s76, v237
	v_min_f32_e32 v154, s76, v238
	v_min_f32_e32 v155, s76, v239
	s_waitcnt lgkmcnt(0)
	v_mfma_f32_16x16x32_bf16 v[236:239], v[204:207], v[48:51], 0
	v_mfma_f32_16x16x32_bf16 v[236:239], v[208:211], v[52:55], v[236:239]
	s_and_b32 s2, s41, 3
	s_lshl_b32 s2, s2, s39
	s_lshr_b32 s3, s41, 2
	s_add_i32 s2, s2, s3
	s_lshl_b32 s2, s2, 7
	s_add_u32 s74, s26, s2
	s_addc_u32 s75, s27, 0
	s_add_i32 s2, s40, 64
	v_add_u32_e32 v137, s2, v164
	v_med3_i32 v137, v137, 0, s38
	v_lshl_add_u32 v137, v137, 9, v162
	global_load_dwordx4 v[32:35], v137, s[74:75]
	s_add_i32 s2, s40, 72
	v_add_u32_e32 v137, s2, v164
	v_med3_i32 v137, v137, 0, s38
	v_lshl_add_u32 v137, v137, 9, v162
	global_load_dwordx4 v[36:39], v137, s[74:75]
	s_waitcnt vmcnt(22)
	ds_write_b128 v165, v[120:123]
	ds_write_b128 v165, v[124:127] offset:1152
	ds_read_b128 v[212:215], v175 offset:2304
	ds_read_b128 v[216:219], v175 offset:2368
	v_mul_f32_e32 v152, s72, v152
	v_mul_f32_e32 v153, s72, v153
	v_mul_f32_e32 v154, s72, v154
	v_mul_f32_e32 v155, s72, v155
	v_exp_f32_e32 v152, v152
	v_exp_f32_e32 v153, v153
	v_exp_f32_e32 v154, v154
	v_exp_f32_e32 v155, v155
	v_add_f32_e32 v138, v138, v152
	v_add_f32_e32 v139, v139, v153
	v_add_f32_e32 v138, v138, v154
	v_add_f32_e32 v139, v139, v155
	v_cvt_pk_bf16_f32 v116, v152, v153
	v_cvt_pk_bf16_f32 v117, v154, v155
	s_add_i32 s77, s40, -16
	s_cmp_lt_u32 s77, s44
	s_cselect_b32 s76, s70, s71
	v_min_f32_e32 v152, s76, v240
	v_min_f32_e32 v153, s76, v241
	v_min_f32_e32 v154, s76, v242
	v_min_f32_e32 v155, s76, v243
	s_waitcnt lgkmcnt(0)
	v_mfma_f32_16x16x32_bf16 v[240:243], v[212:215], v[48:51], 0
	v_mfma_f32_16x16x32_bf16 v[240:243], v[216:219], v[52:55], v[240:243]
	s_waitcnt vmcnt(20)
	ds_write_b128 v165, v[192:195] offset:2304
	ds_write_b128 v165, v[196:199] offset:3456
	ds_read_b128 v[220:223], v175
	ds_read_b128 v[224:227], v175 offset:64
	v_mul_f32_e32 v152, s72, v152
	v_mul_f32_e32 v153, s72, v153
	v_mul_f32_e32 v154, s72, v154
	v_mul_f32_e32 v155, s72, v155
	v_exp_f32_e32 v152, v152
	v_exp_f32_e32 v153, v153
	v_exp_f32_e32 v154, v154
	v_exp_f32_e32 v155, v155
	v_add_f32_e32 v138, v138, v152
	v_add_f32_e32 v139, v139, v153
	v_add_f32_e32 v138, v138, v154
	v_add_f32_e32 v139, v139, v155
	v_cvt_pk_bf16_f32 v118, v152, v153
	v_cvt_pk_bf16_f32 v119, v154, v155
	s_add_i32 s77, s40, 0
	s_cmp_lt_u32 s77, s44
	s_cselect_b32 s76, s70, s71
	v_min_f32_e32 v152, s76, v236
	v_min_f32_e32 v153, s76, v237
	v_min_f32_e32 v154, s76, v238
	v_min_f32_e32 v155, s76, v239
	s_waitcnt lgkmcnt(0)
	v_mfma_f32_16x16x32_bf16 v[236:239], v[220:223], v[48:51], 0
	v_mfma_f32_16x16x32_bf16 v[236:239], v[224:227], v[52:55], v[236:239]
	s_waitcnt vmcnt(6)
	ds_write_b128 v165, v[0:3]
	ds_write_b128 v165, v[4:7] offset:1152
	ds_read_b128 v[228:231], v175 offset:2304
	ds_read_b128 v[232:235], v175 offset:2368
	v_mul_f32_e32 v152, s72, v152
	v_mul_f32_e32 v153, s72, v153
	v_mul_f32_e32 v154, s72, v154
	v_mul_f32_e32 v155, s72, v155
	v_exp_f32_e32 v152, v152
	v_exp_f32_e32 v153, v153
	v_exp_f32_e32 v154, v154
	v_exp_f32_e32 v155, v155
	v_add_f32_e32 v138, v138, v152
	v_add_f32_e32 v139, v139, v153
	v_add_f32_e32 v138, v138, v154
	v_add_f32_e32 v139, v139, v155
	v_cvt_pk_bf16_f32 v120, v152, v153
	v_cvt_pk_bf16_f32 v121, v154, v155
	s_add_i32 s77, s40, 16
	s_cmp_lt_u32 s77, s44
	s_cselect_b32 s76, s70, s71
	v_min_f32_e32 v152, s76, v240
	v_min_f32_e32 v153, s76, v241
	v_min_f32_e32 v154, s76, v242
	v_min_f32_e32 v155, s76, v243
	s_waitcnt lgkmcnt(0)
	v_mfma_f32_16x16x32_bf16 v[240:243], v[228:231], v[48:51], 0
	v_mfma_f32_16x16x32_bf16 v[240:243], v[232:235], v[52:55], v[240:243]
	ds_read_b128 v[204:207], v175
	ds_read_b128 v[208:211], v175 offset:64
	v_mul_f32_e32 v152, s72, v152
	v_mul_f32_e32 v153, s72, v153
	v_mul_f32_e32 v154, s72, v154
	v_mul_f32_e32 v155, s72, v155
	v_exp_f32_e32 v152, v152
	v_exp_f32_e32 v153, v153
	v_exp_f32_e32 v154, v154
	v_exp_f32_e32 v155, v155
	v_add_f32_e32 v138, v138, v152
	v_add_f32_e32 v139, v139, v153
	v_add_f32_e32 v138, v138, v154
	v_add_f32_e32 v139, v139, v155
	v_cvt_pk_bf16_f32 v122, v152, v153
	v_cvt_pk_bf16_f32 v123, v154, v155
	s_add_i32 s77, s40, 32
	s_cmp_lt_u32 s77, s44
	s_cselect_b32 s76, s70, s71
	v_min_f32_e32 v152, s76, v236
	v_min_f32_e32 v153, s76, v237
	v_min_f32_e32 v154, s76, v238
	v_min_f32_e32 v155, s76, v239
	s_waitcnt lgkmcnt(0)
	v_mfma_f32_16x16x32_bf16 v[236:239], v[204:207], v[48:51], 0
	v_mfma_f32_16x16x32_bf16 v[236:239], v[208:211], v[52:55], v[236:239]
	v_mul_f32_e32 v152, s72, v152
	v_mul_f32_e32 v153, s72, v153
	v_mul_f32_e32 v154, s72, v154
	v_mul_f32_e32 v155, s72, v155
	v_exp_f32_e32 v152, v152
	v_exp_f32_e32 v153, v153
	v_exp_f32_e32 v154, v154
	v_exp_f32_e32 v155, v155
	v_add_f32_e32 v138, v138, v152
	v_add_f32_e32 v139, v139, v153
	v_add_f32_e32 v138, v138, v154
	v_add_f32_e32 v139, v139, v155
	v_cvt_pk_bf16_f32 v124, v152, v153
	v_cvt_pk_bf16_f32 v125, v154, v155
	s_add_i32 s77, s40, 48
	s_cmp_lt_u32 s77, s44
	s_cselect_b32 s76, s70, s71
	v_min_f32_e32 v152, s76, v240
	v_min_f32_e32 v153, s76, v241
	v_min_f32_e32 v154, s76, v242
	v_min_f32_e32 v155, s76, v243
	v_mul_f32_e32 v152, s72, v152
	v_mul_f32_e32 v153, s72, v153
	v_mul_f32_e32 v154, s72, v154
	v_mul_f32_e32 v155, s72, v155
	v_exp_f32_e32 v152, v152
	v_exp_f32_e32 v153, v153
	v_exp_f32_e32 v154, v154
	v_exp_f32_e32 v155, v155
	v_add_f32_e32 v138, v138, v152
	v_add_f32_e32 v139, v139, v153
	v_add_f32_e32 v138, v138, v154
	v_add_f32_e32 v139, v139, v155
	v_cvt_pk_bf16_f32 v126, v152, v153
	v_cvt_pk_bf16_f32 v127, v154, v155
	s_add_i32 s77, s40, 64
	s_cmp_lt_u32 s77, s44
	s_cselect_b32 s76, s70, s71
	v_min_f32_e32 v152, s76, v236
	v_min_f32_e32 v153, s76, v237
	v_min_f32_e32 v154, s76, v238
	v_min_f32_e32 v155, s76, v239
	v_mul_f32_e32 v152, s72, v152
	v_mul_f32_e32 v153, s72, v153
	v_mul_f32_e32 v154, s72, v154
	v_mul_f32_e32 v155, s72, v155
	v_exp_f32_e32 v152, v152
	v_exp_f32_e32 v153, v153
	v_exp_f32_e32 v154, v154
	v_exp_f32_e32 v155, v155
	v_cndmask_b32_e64 v152, 0, v152, s[62:63]
	v_cndmask_b32_e64 v153, 0, v153, s[64:65]
	v_cndmask_b32_e64 v154, 0, v154, s[66:67]
	v_cndmask_b32_e64 v155, 0, v155, s[68:69]
	v_add_f32_e32 v138, v138, v152
	v_add_f32_e32 v139, v139, v153
	v_add_f32_e32 v138, v138, v154
	v_add_f32_e32 v139, v139, v155
	v_cvt_pk_bf16_f32 v128, v152, v153
	v_cvt_pk_bf16_f32 v129, v154, v155
	v_add_f32_e32 v132, v138, v139
	v_add_u32_e32 v134, s42, v160
	v_lshlrev_b32_e32 v134, 4, v134
	v_add_u32_e32 v134, s43, v134
	v_subrev_u32_e32 v135, s15, v134
	v_lshrrev_b32_e32 v136, 4, v135
	v_add_u32_e32 v136, v136, v135
	v_mad_u32_u24 v176, v136, s79, v161
	v_lshl_add_u32 v177, v135, 2, s80
	s_and_b32 s2, s43, 3
	s_lshl_b32 s2, s2, s13
	s_lshr_b32 s3, s43, 2
	s_add_i32 s2, s2, s3
	s_lshl_b32 s2, s2, 7
	s_add_u32 s86, s20, s2
	s_addc_u32 s87, s21, 0
	s_add_i32 s2, s42, -64
	v_add_u32_e32 v136, s2, v164
	v_med3_i32 v136, v136, 0, s14
	v_lshl_add_u32 v136, v136, 9, v162
	global_load_dwordx4 v[0:3], v136, s[86:87]
	s_add_i32 s2, s42, -56
	v_add_u32_e32 v135, s2, v164
	v_med3_i32 v135, v135, 0, s14
	v_lshl_add_u32 v135, v135, 9, v162
	global_load_dwordx4 v[4:7], v135, s[86:87]
	s_add_i32 s2, s42, -48
	v_add_u32_e32 v136, s2, v164
	v_med3_i32 v136, v136, 0, s14
	v_lshl_add_u32 v136, v136, 9, v162
	global_load_dwordx4 v[8:11], v136, s[86:87]
	s_add_i32 s2, s42, -40
	v_add_u32_e32 v135, s2, v164
	v_med3_i32 v135, v135, 0, s14
	v_lshl_add_u32 v135, v135, 9, v162
	global_load_dwordx4 v[12:15], v135, s[86:87]
	ds_bpermute_b32 v142, v167, v132
	ds_write_b128 v165, v[64:67]
	ds_write_b128 v165, v[68:71] offset:1152
	ds_write_b128 v165, v[72:75] offset:2304
	ds_write_b128 v165, v[76:79] offset:3456
	s_waitcnt lgkmcnt(0)
	v_add_f32_e32 v132, v132, v142
	ds_bpermute_b32 v142, v168, v132
	ds_read_b64_tr_b16 v[236:237], v166
	ds_read_b64_tr_b16 v[238:239], v166 offset:2304
	ds_read_b64_tr_b16 v[240:241], v166 offset:32
	ds_read_b64_tr_b16 v[242:243], v166 offset:2336
	ds_read_b64_tr_b16 v[244:245], v166 offset:64
	ds_read_b64_tr_b16 v[246:247], v166 offset:2368
	ds_read_b64_tr_b16 v[248:249], v166 offset:96
	ds_read_b64_tr_b16 v[250:251], v166 offset:2400
	s_waitcnt lgkmcnt(0)
	v_add_f32_e32 v132, v132, v142
	ds_write_b128 v165, v[80:83]
	ds_write_b128 v165, v[84:87] offset:1152
	ds_write_b128 v165, v[88:91] offset:2304
	ds_write_b128 v165, v[92:95] offset:3456
	v_mfma_f32_16x16x32_bf16 v[204:207], v[236:239], v[112:115], 0
	v_mfma_f32_16x16x32_bf16 v[208:211], v[240:243], v[112:115], 0
	v_mfma_f32_16x16x32_bf16 v[212:215], v[244:247], v[112:115], 0
	v_mfma_f32_16x16x32_bf16 v[216:219], v[248:251], v[112:115], 0
	s_waitcnt lgkmcnt(0)
	ds_read_b64_tr_b16 v[236:237], v166
	ds_read_b64_tr_b16 v[238:239], v166 offset:2304
	ds_read_b64_tr_b16 v[240:241], v166 offset:32
	ds_read_b64_tr_b16 v[242:243], v166 offset:2336
	ds_read_b64_tr_b16 v[244:245], v166 offset:64
	ds_read_b64_tr_b16 v[246:247], v166 offset:2368
	ds_read_b64_tr_b16 v[248:249], v166 offset:96
	ds_read_b64_tr_b16 v[250:251], v166 offset:2400
	s_waitcnt lgkmcnt(0)
	ds_write_b128 v165, v[96:99]
	ds_write_b128 v165, v[100:103] offset:1152
	ds_write_b128 v165, v[104:107] offset:2304
	ds_write_b128 v165, v[108:111] offset:3456
	v_mfma_f32_16x16x32_bf16 v[204:207], v[236:239], v[116:119], v[204:207]
	v_mfma_f32_16x16x32_bf16 v[208:211], v[240:243], v[116:119], v[208:211]
	v_mfma_f32_16x16x32_bf16 v[212:215], v[244:247], v[116:119], v[212:215]
	v_mfma_f32_16x16x32_bf16 v[216:219], v[248:251], v[116:119], v[216:219]
	s_waitcnt lgkmcnt(0)
	ds_read_b64_tr_b16 v[236:237], v166
	ds_read_b64_tr_b16 v[238:239], v166 offset:2304
	ds_read_b64_tr_b16 v[240:241], v166 offset:32
	ds_read_b64_tr_b16 v[242:243], v166 offset:2336
	ds_read_b64_tr_b16 v[244:245], v166 offset:64
	ds_read_b64_tr_b16 v[246:247], v166 offset:2368
	ds_read_b64_tr_b16 v[248:249], v166 offset:96
	ds_read_b64_tr_b16 v[250:251], v166 offset:2400
	s_waitcnt lgkmcnt(0)
	s_waitcnt vmcnt(6)
	ds_write_b128 v165, v[16:19]
	ds_write_b128 v165, v[20:23] offset:1152
	ds_write_b128 v165, v[24:27] offset:2304
	ds_write_b128 v165, v[28:31] offset:3456
	v_mfma_f32_16x16x32_bf16 v[204:207], v[236:239], v[120:123], v[204:207]
	v_mfma_f32_16x16x32_bf16 v[208:211], v[240:243], v[120:123], v[208:211]
	v_mfma_f32_16x16x32_bf16 v[212:215], v[244:247], v[120:123], v[212:215]
	v_mfma_f32_16x16x32_bf16 v[216:219], v[248:251], v[120:123], v[216:219]
	s_waitcnt lgkmcnt(0)
	ds_read_b64_tr_b16 v[236:237], v166
	ds_read_b64_tr_b16 v[238:239], v166 offset:2304
	ds_read_b64_tr_b16 v[240:241], v166 offset:32
	ds_read_b64_tr_b16 v[242:243], v166 offset:2336
	ds_read_b64_tr_b16 v[244:245], v166 offset:64
	ds_read_b64_tr_b16 v[246:247], v166 offset:2368
	ds_read_b64_tr_b16 v[248:249], v166 offset:96
	ds_read_b64_tr_b16 v[250:251], v166 offset:2400
	s_waitcnt lgkmcnt(0)
	s_add_i32 s2, s42, -32
	v_add_u32_e32 v136, s2, v164
	v_med3_i32 v136, v136, 0, s14
	v_lshl_add_u32 v136, v136, 9, v162
	global_load_dwordx4 v[16:19], v136, s[86:87]
	s_add_i32 s2, s42, -24
	v_add_u32_e32 v135, s2, v164
	v_med3_i32 v135, v135, 0, s14
	v_lshl_add_u32 v135, v135, 9, v162
	global_load_dwordx4 v[20:23], v135, s[86:87]
	s_add_i32 s2, s42, -16
	v_add_u32_e32 v136, s2, v164
	v_med3_i32 v136, v136, 0, s14
	v_lshl_add_u32 v136, v136, 9, v162
	global_load_dwordx4 v[24:27], v136, s[86:87]
	s_add_i32 s2, s42, -8
	v_add_u32_e32 v135, s2, v164
	v_med3_i32 v135, v135, 0, s14
	v_lshl_add_u32 v135, v135, 9, v162
	global_load_dwordx4 v[28:31], v135, s[86:87]
	s_waitcnt vmcnt(8)
	ds_write_b128 v165, v[32:35]
	ds_write_b128 v165, v[36:39] offset:1152
	v_mfma_f32_16x16x32_bf16 v[204:207], v[236:239], v[124:127], v[204:207]
	v_mfma_f32_16x16x32_bf16 v[208:211], v[240:243], v[124:127], v[208:211]
	v_mfma_f32_16x16x32_bf16 v[212:215], v[244:247], v[124:127], v[212:215]
	v_mfma_f32_16x16x32_bf16 v[216:219], v[248:251], v[124:127], v[216:219]
	s_waitcnt lgkmcnt(0)
	ds_read_b64_tr_b16 v[236:237], v166
	ds_read_b64_tr_b16 v[238:239], v166 offset:2304
	ds_read_b64_tr_b16 v[240:241], v166 offset:32
	ds_read_b64_tr_b16 v[242:243], v166 offset:2336
	ds_read_b64_tr_b16 v[244:245], v166 offset:64
	ds_read_b64_tr_b16 v[246:247], v166 offset:2368
	ds_read_b64_tr_b16 v[248:249], v166 offset:96
	ds_read_b64_tr_b16 v[250:251], v166 offset:2400
	s_waitcnt lgkmcnt(0)
	s_add_i32 s2, s42, 0
	v_add_u32_e32 v136, s2, v164
	v_med3_i32 v136, v136, 0, s14
	v_lshl_add_u32 v136, v136, 9, v162
	global_load_dwordx4 v[32:35], v136, s[86:87]
	s_add_i32 s2, s42, 8
	v_add_u32_e32 v135, s2, v164
	v_med3_i32 v135, v135, 0, s14
	v_lshl_add_u32 v135, v135, 9, v162
	global_load_dwordx4 v[36:39], v135, s[86:87]
	s_add_i32 s2, s42, 16
	v_add_u32_e32 v136, s2, v164
	v_med3_i32 v136, v136, 0, s14
	v_lshl_add_u32 v136, v136, 9, v162
	global_load_dwordx4 v[40:43], v136, s[86:87]
	s_add_i32 s2, s42, 24
	v_add_u32_e32 v135, s2, v164
	v_med3_i32 v135, v135, 0, s14
	v_lshl_add_u32 v135, v135, 9, v162
	global_load_dwordx4 v[44:47], v135, s[86:87]
	v_mfma_f32_16x16x32_bf16 v[204:207], v[236:239], v[128:131], v[204:207]
	v_mfma_f32_16x16x32_bf16 v[208:211], v[240:243], v[128:131], v[208:211]
	v_mfma_f32_16x16x32_bf16 v[212:215], v[244:247], v[128:131], v[212:215]
	v_mfma_f32_16x16x32_bf16 v[216:219], v[248:251], v[128:131], v[216:219]
	s_add_i32 s2, s42, 32
	v_add_u32_e32 v136, s2, v164
	v_med3_i32 v136, v136, 0, s14
	v_lshl_add_u32 v136, v136, 9, v162
	global_load_dwordx4 v[120:123], v136, s[86:87]
	s_add_i32 s2, s42, 40
	v_add_u32_e32 v135, s2, v164
	v_med3_i32 v135, v135, 0, s14
	v_lshl_add_u32 v135, v135, 9, v162
	global_load_dwordx4 v[124:127], v135, s[86:87]
	s_add_i32 s2, s42, 48
	v_add_u32_e32 v136, s2, v164
	v_med3_i32 v136, v136, 0, s14
	v_lshl_add_u32 v136, v136, 9, v162
	global_load_dwordx4 v[192:195], v136, s[86:87]
	s_add_i32 s2, s42, 56
	v_add_u32_e32 v135, s2, v164
	v_med3_i32 v135, v135, 0, s14
	v_lshl_add_u32 v135, v135, 9, v162
	global_load_dwordx4 v[196:199], v135, s[86:87]
	s_and_b32 s2, s43, 3
	s_lshl_b32 s2, s2, s13
	s_lshr_b32 s3, s43, 2
	s_add_i32 s2, s2, s3
	s_lshl_b32 s2, s2, 7
	s_add_u32 s74, s22, s2
	s_addc_u32 s75, s23, 0
	s_add_i32 s2, s42, -64
	v_add_u32_e32 v137, s2, v164
	v_med3_i32 v137, v137, 0, s14
	v_lshl_add_u32 v137, v137, 9, v162
	global_load_dwordx4 v[64:67], v137, s[74:75]
	s_add_i32 s2, s42, -56
	v_add_u32_e32 v137, s2, v164
	v_med3_i32 v137, v137, 0, s14
	v_lshl_add_u32 v137, v137, 9, v162
	global_load_dwordx4 v[68:71], v137, s[74:75]
	s_add_i32 s2, s42, -48
	v_add_u32_e32 v137, s2, v164
	v_med3_i32 v137, v137, 0, s14
	v_lshl_add_u32 v137, v137, 9, v162
	global_load_dwordx4 v[72:75], v137, s[74:75]
	s_add_i32 s2, s42, -40
	v_add_u32_e32 v137, s2, v164
	v_med3_i32 v137, v137, 0, s14
	v_lshl_add_u32 v137, v137, 9, v162
	global_load_dwordx4 v[76:79], v137, s[74:75]
	s_and_b32 s2, s43, 3
	s_lshl_b32 s2, s2, s13
	s_lshr_b32 s3, s43, 2
	s_add_i32 s2, s2, s3
	s_lshl_b32 s2, s2, 7
	s_add_u32 s74, s22, s2
	s_addc_u32 s75, s23, 0
	s_add_i32 s2, s42, -32
	v_add_u32_e32 v137, s2, v164
	v_med3_i32 v137, v137, 0, s14
	v_lshl_add_u32 v137, v137, 9, v162
	global_load_dwordx4 v[80:83], v137, s[74:75]
	s_add_i32 s2, s42, -24
	v_add_u32_e32 v137, s2, v164
	v_med3_i32 v137, v137, 0, s14
	v_lshl_add_u32 v137, v137, 9, v162
	global_load_dwordx4 v[84:87], v137, s[74:75]
	s_add_i32 s2, s42, -16
	v_add_u32_e32 v137, s2, v164
	v_med3_i32 v137, v137, 0, s14
	v_lshl_add_u32 v137, v137, 9, v162
	global_load_dwordx4 v[88:91], v137, s[74:75]
	s_add_i32 s2, s42, -8
	v_add_u32_e32 v137, s2, v164
	v_med3_i32 v137, v137, 0, s14
	v_lshl_add_u32 v137, v137, 9, v162
	global_load_dwordx4 v[92:95], v137, s[74:75]
	s_and_b32 s2, s43, 3
	s_lshl_b32 s2, s2, s13
	s_lshr_b32 s3, s43, 2
	s_add_i32 s2, s2, s3
	s_lshl_b32 s2, s2, 7
	s_add_u32 s74, s22, s2
	s_addc_u32 s75, s23, 0
	s_add_i32 s2, s42, 0
	v_add_u32_e32 v137, s2, v164
	v_med3_i32 v137, v137, 0, s14
	v_lshl_add_u32 v137, v137, 9, v162
	global_load_dwordx4 v[96:99], v137, s[74:75]
	s_add_i32 s2, s42, 8
	v_add_u32_e32 v137, s2, v164
	v_med3_i32 v137, v137, 0, s14
	v_lshl_add_u32 v137, v137, 9, v162
	global_load_dwordx4 v[100:103], v137, s[74:75]
	s_add_i32 s2, s42, 16
	v_add_u32_e32 v137, s2, v164
	v_med3_i32 v137, v137, 0, s14
	v_lshl_add_u32 v137, v137, 9, v162
	global_load_dwordx4 v[104:107], v137, s[74:75]
	s_add_i32 s2, s42, 24
	v_add_u32_e32 v137, s2, v164
	v_med3_i32 v137, v137, 0, s14
	v_lshl_add_u32 v137, v137, 9, v162
	global_load_dwordx4 v[108:111], v137, s[74:75]
	ds_read_b128 v[236:239], v173 offset:0
	ds_read_b128 v[240:243], v173 offset:64
	ds_read_b128 v[244:247], v173 offset:128
	ds_read_b128 v[248:251], v173 offset:192
	ds_read_b32 v142, v174 offset:0
	s_waitcnt lgkmcnt(0)
	v_add_f32_e32 v204, v236, v204
	v_add_f32_e32 v205, v237, v205
	v_add_f32_e32 v206, v238, v206
	v_add_f32_e32 v207, v239, v207
	v_add_f32_e32 v208, v240, v208
	v_add_f32_e32 v209, v241, v209
	v_add_f32_e32 v210, v242, v210
	v_add_f32_e32 v211, v243, v211
	v_add_f32_e32 v212, v244, v212
	v_add_f32_e32 v213, v245, v213
	v_add_f32_e32 v214, v246, v214
	v_add_f32_e32 v215, v247, v215
	v_add_f32_e32 v216, v248, v216
	v_add_f32_e32 v217, v249, v217
	v_add_f32_e32 v218, v250, v218
	v_add_f32_e32 v219, v251, v219
	v_add_f32_e32 v132, v142, v132
	ds_write_b128 v173, v[204:207] offset:0
	ds_write_b128 v173, v[208:211] offset:64
	ds_write_b128 v173, v[212:215] offset:128
	ds_write_b128 v173, v[216:219] offset:192
	ds_write_b32 v174, v132 offset:0
	s_mov_b32 s40, s42
	s_mov_b32 s41, s43
	v_mov_b32_e32 v173, v176
	v_mov_b32_e32 v174, v177
	s_lshr_b32 s44, s33, 4
	s_add_i32 s45, s10, s8
	s_cmp_lt_u32 s45, 0x800
	s_cbranch_scc1 .Latt_newunit
	s_mov_b32 s37, 1
	s_branch .Latt_ud_done

.Latt_ud_done:
	s_lshl_b32 s2, s0, 5
	s_add_i32 s42, s15, s2
	s_mov_b32 s43, 0
	v_subrev_u32_e32 v143, s80, v174
	v_lshl_add_u32 v143, v143, 5, v161
	v_add_u32_e32 v143, 0x1b500, v143
	ds_read_b128 v[48:51], v143
	ds_read_b128 v[52:55], v143 offset:64
	s_waitcnt lgkmcnt(0)
	v_mov_b32_e32 v138, 0
	v_mov_b32_e32 v139, 0
	s_waitcnt vmcnt(24)
	ds_write_b128 v165, v[0:3]
	ds_write_b128 v165, v[4:7] offset:1152
	ds_write_b128 v165, v[8:11] offset:2304
	ds_write_b128 v165, v[12:15] offset:3456
	s_waitcnt lgkmcnt(0)
	ds_read_b128 v[204:207], v175
	ds_read_b128 v[208:211], v175 offset:64
	ds_read_b128 v[212:215], v175 offset:2304
	ds_read_b128 v[216:219], v175 offset:2368
	s_and_b32 s2, s41, 3
	s_lshl_b32 s2, s2, s39
	s_lshr_b32 s3, s41, 2
	s_add_i32 s2, s2, s3
	s_lshl_b32 s2, s2, 7
	s_add_u32 s86, s24, s2
	s_addc_u32 s87, s25, 0
	s_add_i32 s2, s40, 64
	v_add_u32_e32 v136, s2, v164
	v_med3_i32 v136, v136, 0, s38
	v_lshl_add_u32 v136, v136, 9, v162
	global_load_dwordx4 v[0:3], v136, s[86:87]
	s_add_i32 s2, s40, 72
	v_add_u32_e32 v135, s2, v164
	v_med3_i32 v135, v135, 0, s38
	v_lshl_add_u32 v135, v135, 9, v162
	global_load_dwordx4 v[4:7], v135, s[86:87]
	s_waitcnt vmcnt(22)
	s_waitcnt lgkmcnt(0)
	ds_write_b128 v165, v[16:19]
	ds_write_b128 v165, v[20:23] offset:1152
	ds_write_b128 v165, v[24:27] offset:2304
	ds_write_b128 v165, v[28:31] offset:3456
	v_mfma_f32_16x16x32_bf16 v[236:239], v[204:207], v[48:51], 0
	v_mfma_f32_16x16x32_bf16 v[236:239], v[208:211], v[52:55], v[236:239]
	v_mfma_f32_16x16x32_bf16 v[240:243], v[212:215], v[48:51], 0
	v_mfma_f32_16x16x32_bf16 v[240:243], v[216:219], v[52:55], v[240:243]
	s_waitcnt lgkmcnt(0)
	ds_read_b128 v[220:223], v175
	ds_read_b128 v[224:227], v175 offset:64
	s_and_b32 s2, s41, 3
	s_lshl_b32 s2, s2, s39
	s_lshr_b32 s3, s41, 2
	s_add_i32 s2, s2, s3
	s_lshl_b32 s2, s2, 7
	s_add_u32 s74, s26, s2
	s_addc_u32 s75, s27, 0
	s_add_i32 s2, s40, 32
	v_add_u32_e32 v137, s2, v164
	v_med3_i32 v137, v137, 0, s38
	v_lshl_add_u32 v137, v137, 9, v162
	global_load_dwordx4 v[16:19], v137, s[74:75]
	s_add_i32 s2, s40, 40
	v_add_u32_e32 v137, s2, v164
	v_med3_i32 v137, v137, 0, s38
	v_lshl_add_u32 v137, v137, 9, v162
	global_load_dwordx4 v[20:23], v137, s[74:75]
	s_add_i32 s2, s40, 48
	v_add_u32_e32 v137, s2, v164
	v_med3_i32 v137, v137, 0, s38
	v_lshl_add_u32 v137, v137, 9, v162
	global_load_dwordx4 v[24:27], v137, s[74:75]
	s_add_i32 s2, s40, 56
	v_add_u32_e32 v137, s2, v164
	v_med3_i32 v137, v137, 0, s38
	v_lshl_add_u32 v137, v137, 9, v162
	global_load_dwordx4 v[28:31], v137, s[74:75]
	s_nop 7
	s_add_i32 s77, s40, -64
	s_cmp_lt_u32 s77, s44
	s_cselect_b32 s76, s70, s71
	v_min_f32_e32 v152, s76, v236
	v_min_f32_e32 v153, s76, v237
	v_min_f32_e32 v154, s76, v238
	v_min_f32_e32 v155, s76, v239
	s_waitcnt lgkmcnt(0)
	v_mfma_f32_16x16x32_bf16 v[236:239], v[220:223], v[48:51], 0
	v_mfma_f32_16x16x32_bf16 v[236:239], v[224:227], v[52:55], v[236:239]
	s_waitcnt vmcnt(24)
	ds_write_b128 v165, v[32:35]
	ds_write_b128 v165, v[36:39] offset:1152
	ds_read_b128 v[228:231], v175 offset:2304
	ds_read_b128 v[232:235], v175 offset:2368
	v_mul_f32_e32 v152, s72, v152
	v_mul_f32_e32 v153, s72, v153
	v_mul_f32_e32 v154, s72, v154
	v_mul_f32_e32 v155, s72, v155
	v_exp_f32_e32 v152, v152
	v_exp_f32_e32 v153, v153
	v_exp_f32_e32 v154, v154
	v_exp_f32_e32 v155, v155
	v_cndmask_b32_e64 v152, 0, v152, s[54:55]
	v_cndmask_b32_e64 v153, 0, v153, s[56:57]
	v_cndmask_b32_e64 v154, 0, v154, s[58:59]
	v_cndmask_b32_e64 v155, 0, v155, s[60:61]
	v_add_f32_e32 v138, v138, v152
	v_add_f32_e32 v139, v139, v153
	v_add_f32_e32 v138, v138, v154
	v_add_f32_e32 v139, v139, v155
	v_cvt_pk_bf16_f32 v112, v152, v153
	v_cvt_pk_bf16_f32 v113, v154, v155
	s_add_i32 s77, s40, -48
	s_cmp_lt_u32 s77, s44
	s_cselect_b32 s76, s70, s71
	v_min_f32_e32 v152, s76, v240
	v_min_f32_e32 v153, s76, v241
	v_min_f32_e32 v154, s76, v242
	v_min_f32_e32 v155, s76, v243
	s_waitcnt lgkmcnt(0)
	v_mfma_f32_16x16x32_bf16 v[240:243], v[228:231], v[48:51], 0
	v_mfma_f32_16x16x32_bf16 v[240:243], v[232:235], v[52:55], v[240:243]
	s_waitcnt vmcnt(22)
	ds_write_b128 v165, v[40:43] offset:2304
	ds_write_b128 v165, v[44:47] offset:3456
	ds_read_b128 v[204:207], v175
	ds_read_b128 v[208:211], v175 offset:64
	v_mul_f32_e32 v152, s72, v152
	v_mul_f32_e32 v153, s72, v153
	v_mul_f32_e32 v154, s72, v154
	v_mul_f32_e32 v155, s72, v155
	v_exp_f32_e32 v152, v152
	v_exp_f32_e32 v153, v153
	v_exp_f32_e32 v154, v154
	v_exp_f32_e32 v155, v155
	v_add_f32_e32 v138, v138, v152
	v_add_f32_e32 v139, v139, v153
	v_add_f32_e32 v138, v138, v154
	v_add_f32_e32 v139, v139, v155
	v_cvt_pk_bf16_f32 v114, v152, v153
	v_cvt_pk_bf16_f32 v115, v154, v155
	s_add_i32 s77, s40, -32
	s_cmp_lt_u32 s77, s44
	s_cselect_b32 s76, s70, s71
	v_min_f32_e32 v152, s76, v236
	v_min_f32_e32 v153, s76, v237
	v_min_f32_e32 v154, s76, v238
	v_min_f32_e32 v155, s76, v239
	s_waitcnt lgkmcnt(0)
	v_mfma_f32_16x16x32_bf16 v[236:239], v[204:207], v[48:51], 0
	v_mfma_f32_16x16x32_bf16 v[236:239], v[208:211], v[52:55], v[236:239]
	s_and_b32 s2, s41, 3
	s_lshl_b32 s2, s2, s39
	s_lshr_b32 s3, s41, 2
	s_add_i32 s2, s2, s3
	s_lshl_b32 s2, s2, 7
	s_add_u32 s74, s26, s2
	s_addc_u32 s75, s27, 0
	s_add_i32 s2, s40, 64
	v_add_u32_e32 v137, s2, v164
	v_med3_i32 v137, v137, 0, s38
	v_lshl_add_u32 v137, v137, 9, v162
	global_load_dwordx4 v[32:35], v137, s[74:75]
	s_add_i32 s2, s40, 72
	v_add_u32_e32 v137, s2, v164
	v_med3_i32 v137, v137, 0, s38
	v_lshl_add_u32 v137, v137, 9, v162
	global_load_dwordx4 v[36:39], v137, s[74:75]
	s_waitcnt vmcnt(22)
	ds_write_b128 v165, v[120:123]
	ds_write_b128 v165, v[124:127] offset:1152
	ds_read_b128 v[212:215], v175 offset:2304
	ds_read_b128 v[216:219], v175 offset:2368
	v_mul_f32_e32 v152, s72, v152
	v_mul_f32_e32 v153, s72, v153
	v_mul_f32_e32 v154, s72, v154
	v_mul_f32_e32 v155, s72, v155
	v_exp_f32_e32 v152, v152
	v_exp_f32_e32 v153, v153
	v_exp_f32_e32 v154, v154
	v_exp_f32_e32 v155, v155
	v_add_f32_e32 v138, v138, v152
	v_add_f32_e32 v139, v139, v153
	v_add_f32_e32 v138, v138, v154
	v_add_f32_e32 v139, v139, v155
	v_cvt_pk_bf16_f32 v116, v152, v153
	v_cvt_pk_bf16_f32 v117, v154, v155
	s_add_i32 s77, s40, -16
	s_cmp_lt_u32 s77, s44
	s_cselect_b32 s76, s70, s71
	v_min_f32_e32 v152, s76, v240
	v_min_f32_e32 v153, s76, v241
	v_min_f32_e32 v154, s76, v242
	v_min_f32_e32 v155, s76, v243
	s_waitcnt lgkmcnt(0)
	v_mfma_f32_16x16x32_bf16 v[240:243], v[212:215], v[48:51], 0
	v_mfma_f32_16x16x32_bf16 v[240:243], v[216:219], v[52:55], v[240:243]
	s_waitcnt vmcnt(20)
	ds_write_b128 v165, v[192:195] offset:2304
	ds_write_b128 v165, v[196:199] offset:3456
	ds_read_b128 v[220:223], v175
	ds_read_b128 v[224:227], v175 offset:64
	v_mul_f32_e32 v152, s72, v152
	v_mul_f32_e32 v153, s72, v153
	v_mul_f32_e32 v154, s72, v154
	v_mul_f32_e32 v155, s72, v155
	v_exp_f32_e32 v152, v152
	v_exp_f32_e32 v153, v153
	v_exp_f32_e32 v154, v154
	v_exp_f32_e32 v155, v155
	v_add_f32_e32 v138, v138, v152
	v_add_f32_e32 v139, v139, v153
	v_add_f32_e32 v138, v138, v154
	v_add_f32_e32 v139, v139, v155
	v_cvt_pk_bf16_f32 v118, v152, v153
	v_cvt_pk_bf16_f32 v119, v154, v155
	s_add_i32 s77, s40, 0
	s_cmp_lt_u32 s77, s44
	s_cselect_b32 s76, s70, s71
	v_min_f32_e32 v152, s76, v236
	v_min_f32_e32 v153, s76, v237
	v_min_f32_e32 v154, s76, v238
	v_min_f32_e32 v155, s76, v239
	s_waitcnt lgkmcnt(0)
	v_mfma_f32_16x16x32_bf16 v[236:239], v[220:223], v[48:51], 0
	v_mfma_f32_16x16x32_bf16 v[236:239], v[224:227], v[52:55], v[236:239]
	s_waitcnt vmcnt(6)
	ds_write_b128 v165, v[0:3]
	ds_write_b128 v165, v[4:7] offset:1152
	ds_read_b128 v[228:231], v175 offset:2304
	ds_read_b128 v[232:235], v175 offset:2368
	v_mul_f32_e32 v152, s72, v152
	v_mul_f32_e32 v153, s72, v153
	v_mul_f32_e32 v154, s72, v154
	v_mul_f32_e32 v155, s72, v155
	v_exp_f32_e32 v152, v152
	v_exp_f32_e32 v153, v153
	v_exp_f32_e32 v154, v154
	v_exp_f32_e32 v155, v155
	v_add_f32_e32 v138, v138, v152
	v_add_f32_e32 v139, v139, v153
	v_add_f32_e32 v138, v138, v154
	v_add_f32_e32 v139, v139, v155
	v_cvt_pk_bf16_f32 v120, v152, v153
	v_cvt_pk_bf16_f32 v121, v154, v155
	s_add_i32 s77, s40, 16
	s_cmp_lt_u32 s77, s44
	s_cselect_b32 s76, s70, s71
	v_min_f32_e32 v152, s76, v240
	v_min_f32_e32 v153, s76, v241
	v_min_f32_e32 v154, s76, v242
	v_min_f32_e32 v155, s76, v243
	s_waitcnt lgkmcnt(0)
	v_mfma_f32_16x16x32_bf16 v[240:243], v[228:231], v[48:51], 0
	v_mfma_f32_16x16x32_bf16 v[240:243], v[232:235], v[52:55], v[240:243]
	ds_read_b128 v[204:207], v175
	ds_read_b128 v[208:211], v175 offset:64
	v_mul_f32_e32 v152, s72, v152
	v_mul_f32_e32 v153, s72, v153
	v_mul_f32_e32 v154, s72, v154
	v_mul_f32_e32 v155, s72, v155
	v_exp_f32_e32 v152, v152
	v_exp_f32_e32 v153, v153
	v_exp_f32_e32 v154, v154
	v_exp_f32_e32 v155, v155
	v_add_f32_e32 v138, v138, v152
	v_add_f32_e32 v139, v139, v153
	v_add_f32_e32 v138, v138, v154
	v_add_f32_e32 v139, v139, v155
	v_cvt_pk_bf16_f32 v122, v152, v153
	v_cvt_pk_bf16_f32 v123, v154, v155
	s_add_i32 s77, s40, 32
	s_cmp_lt_u32 s77, s44
	s_cselect_b32 s76, s70, s71
	v_min_f32_e32 v152, s76, v236
	v_min_f32_e32 v153, s76, v237
	v_min_f32_e32 v154, s76, v238
	v_min_f32_e32 v155, s76, v239
	s_waitcnt lgkmcnt(0)
	v_mfma_f32_16x16x32_bf16 v[236:239], v[204:207], v[48:51], 0
	v_mfma_f32_16x16x32_bf16 v[236:239], v[208:211], v[52:55], v[236:239]
	v_mul_f32_e32 v152, s72, v152
	v_mul_f32_e32 v153, s72, v153
	v_mul_f32_e32 v154, s72, v154
	v_mul_f32_e32 v155, s72, v155
	v_exp_f32_e32 v152, v152
	v_exp_f32_e32 v153, v153
	v_exp_f32_e32 v154, v154
	v_exp_f32_e32 v155, v155
	v_add_f32_e32 v138, v138, v152
	v_add_f32_e32 v139, v139, v153
	v_add_f32_e32 v138, v138, v154
	v_add_f32_e32 v139, v139, v155
	v_cvt_pk_bf16_f32 v124, v152, v153
	v_cvt_pk_bf16_f32 v125, v154, v155
	s_add_i32 s77, s40, 48
	s_cmp_lt_u32 s77, s44
	s_cselect_b32 s76, s70, s71
	v_min_f32_e32 v152, s76, v240
	v_min_f32_e32 v153, s76, v241
	v_min_f32_e32 v154, s76, v242
	v_min_f32_e32 v155, s76, v243
	v_mul_f32_e32 v152, s72, v152
	v_mul_f32_e32 v153, s72, v153
	v_mul_f32_e32 v154, s72, v154
	v_mul_f32_e32 v155, s72, v155
	v_exp_f32_e32 v152, v152
	v_exp_f32_e32 v153, v153
	v_exp_f32_e32 v154, v154
	v_exp_f32_e32 v155, v155
	v_add_f32_e32 v138, v138, v152
	v_add_f32_e32 v139, v139, v153
	v_add_f32_e32 v138, v138, v154
	v_add_f32_e32 v139, v139, v155
	v_cvt_pk_bf16_f32 v126, v152, v153
	v_cvt_pk_bf16_f32 v127, v154, v155
	s_add_i32 s77, s40, 64
	s_cmp_lt_u32 s77, s44
	s_cselect_b32 s76, s70, s71
	v_min_f32_e32 v152, s76, v236
	v_min_f32_e32 v153, s76, v237
	v_min_f32_e32 v154, s76, v238
	v_min_f32_e32 v155, s76, v239
	v_mul_f32_e32 v152, s72, v152
	v_mul_f32_e32 v153, s72, v153
	v_mul_f32_e32 v154, s72, v154
	v_mul_f32_e32 v155, s72, v155
	v_exp_f32_e32 v152, v152
	v_exp_f32_e32 v153, v153
	v_exp_f32_e32 v154, v154
	v_exp_f32_e32 v155, v155
	v_cndmask_b32_e64 v152, 0, v152, s[62:63]
	v_cndmask_b32_e64 v153, 0, v153, s[64:65]
	v_cndmask_b32_e64 v154, 0, v154, s[66:67]
	v_cndmask_b32_e64 v155, 0, v155, s[68:69]
	v_add_f32_e32 v138, v138, v152
	v_add_f32_e32 v139, v139, v153
	v_add_f32_e32 v138, v138, v154
	v_add_f32_e32 v139, v139, v155
	v_cvt_pk_bf16_f32 v128, v152, v153
	v_cvt_pk_bf16_f32 v129, v154, v155
	v_add_f32_e32 v132, v138, v139
	v_add_u32_e32 v134, s42, v160
	v_add_u32_e32 v134, s43, v134
	v_subrev_u32_e32 v135, s15, v134
	v_lshrrev_b32_e32 v136, 4, v135
	v_add_u32_e32 v136, v136, v135
	v_mad_u32_u24 v176, v136, s79, v161
	v_lshl_add_u32 v177, v135, 2, s80
	s_mul_i32 s2, s0, 48
	s_add_i32 s2, s2, s15
	s_add_i32 s2, s2, -64
	v_add_u32_e32 v138, s2, v164
	v_and_b32_e32 v139, 3, v138
	v_lshlrev_b32_e32 v139, s13, v139
	v_bfe_u32 v140, v138, 2, 2
	v_add_u32_e32 v139, v139, v140
	v_lshl_add_u32 v139, v139, 7, v162
	v_ashrrev_i32_e32 v138, 4, v138
	v_med3_i32 v138, v138, 0, s14
	v_lshl_add_u32 v138, v138, 9, v139
	global_load_dwordx4 v[0:3], v138, s[20:21]
	s_mul_i32 s2, s0, 48
	s_add_i32 s2, s2, s15
	s_add_i32 s2, s2, -56
	v_add_u32_e32 v138, s2, v164
	v_and_b32_e32 v139, 3, v138
	v_lshlrev_b32_e32 v139, s13, v139
	v_bfe_u32 v140, v138, 2, 2
	v_add_u32_e32 v139, v139, v140
	v_lshl_add_u32 v139, v139, 7, v162
	v_ashrrev_i32_e32 v138, 4, v138
	v_med3_i32 v138, v138, 0, s14
	v_lshl_add_u32 v138, v138, 9, v139
	global_load_dwordx4 v[4:7], v138, s[20:21]
	s_mul_i32 s2, s0, 48
	s_add_i32 s2, s2, s15
	s_add_i32 s2, s2, -48
	v_add_u32_e32 v138, s2, v164
	v_and_b32_e32 v139, 3, v138
	v_lshlrev_b32_e32 v139, s13, v139
	v_bfe_u32 v140, v138, 2, 2
	v_add_u32_e32 v139, v139, v140
	v_lshl_add_u32 v139, v139, 7, v162
	v_ashrrev_i32_e32 v138, 4, v138
	v_med3_i32 v138, v138, 0, s14
	v_lshl_add_u32 v138, v138, 9, v139
	global_load_dwordx4 v[8:11], v138, s[20:21]
	s_mul_i32 s2, s0, 48
	s_add_i32 s2, s2, s15
	s_add_i32 s2, s2, -40
	v_add_u32_e32 v138, s2, v164
	v_and_b32_e32 v139, 3, v138
	v_lshlrev_b32_e32 v139, s13, v139
	v_bfe_u32 v140, v138, 2, 2
	v_add_u32_e32 v139, v139, v140
	v_lshl_add_u32 v139, v139, 7, v162
	v_ashrrev_i32_e32 v138, 4, v138
	v_med3_i32 v138, v138, 0, s14
	v_lshl_add_u32 v138, v138, 9, v139
	global_load_dwordx4 v[12:15], v138, s[20:21]
	s_lshl_b32 s2, s0, 5
	s_add_i32 s2, s2, s15
	s_add_i32 s2, s2, 0
	v_add_u32_e32 v138, s2, v164
	v_and_b32_e32 v139, 3, v138
	v_lshlrev_b32_e32 v139, s13, v139
	v_lshrrev_b32_e32 v140, 2, v138
	v_add_u32_e32 v139, v139, v140
	v_lshl_add_u32 v139, v139, 7, v162
	global_load_dwordx4 v[48:51], v139, s[18:19]
	s_lshl_b32 s2, s0, 5
	s_add_i32 s2, s2, s15
	s_add_i32 s2, s2, 8
	v_add_u32_e32 v138, s2, v164
	v_and_b32_e32 v139, 3, v138
	v_lshlrev_b32_e32 v139, s13, v139
	v_lshrrev_b32_e32 v140, 2, v138
	v_add_u32_e32 v139, v139, v140
	v_lshl_add_u32 v139, v139, 7, v162
	global_load_dwordx4 v[52:55], v139, s[18:19]
	s_lshl_b32 s2, s0, 5
	s_add_i32 s2, s2, s15
	s_add_i32 s2, s2, 16
	v_add_u32_e32 v138, s2, v164
	v_and_b32_e32 v139, 3, v138
	v_lshlrev_b32_e32 v139, s13, v139
	v_lshrrev_b32_e32 v140, 2, v138
	v_add_u32_e32 v139, v139, v140
	v_lshl_add_u32 v139, v139, 7, v162
	global_load_dwordx4 v[56:59], v139, s[18:19]
	s_lshl_b32 s2, s0, 5
	s_add_i32 s2, s2, s15
	s_add_i32 s2, s2, 24
	v_add_u32_e32 v138, s2, v164
	v_and_b32_e32 v139, 3, v138
	v_lshlrev_b32_e32 v139, s13, v139
	v_lshrrev_b32_e32 v140, 2, v138
	v_add_u32_e32 v139, v139, v140
	v_lshl_add_u32 v139, v139, 7, v162
	global_load_dwordx4 v[60:63], v139, s[18:19]
	ds_bpermute_b32 v142, v167, v132
	ds_write_b128 v165, v[64:67]
	ds_write_b128 v165, v[68:71] offset:1152
	ds_write_b128 v165, v[72:75] offset:2304
	ds_write_b128 v165, v[76:79] offset:3456
	s_waitcnt lgkmcnt(0)
	v_add_f32_e32 v132, v132, v142
	ds_bpermute_b32 v142, v168, v132
	ds_read_b64_tr_b16 v[236:237], v166
	ds_read_b64_tr_b16 v[238:239], v166 offset:2304
	ds_read_b64_tr_b16 v[240:241], v166 offset:32
	ds_read_b64_tr_b16 v[242:243], v166 offset:2336
	ds_read_b64_tr_b16 v[244:245], v166 offset:64
	ds_read_b64_tr_b16 v[246:247], v166 offset:2368
	ds_read_b64_tr_b16 v[248:249], v166 offset:96
	ds_read_b64_tr_b16 v[250:251], v166 offset:2400
	s_waitcnt lgkmcnt(0)
	v_add_f32_e32 v132, v132, v142
	ds_write_b128 v165, v[80:83]
	ds_write_b128 v165, v[84:87] offset:1152
	ds_write_b128 v165, v[88:91] offset:2304
	ds_write_b128 v165, v[92:95] offset:3456
	v_mfma_f32_16x16x32_bf16 v[204:207], v[236:239], v[112:115], 0
	v_mfma_f32_16x16x32_bf16 v[208:211], v[240:243], v[112:115], 0
	v_mfma_f32_16x16x32_bf16 v[212:215], v[244:247], v[112:115], 0
	v_mfma_f32_16x16x32_bf16 v[216:219], v[248:251], v[112:115], 0
	s_waitcnt lgkmcnt(0)
	ds_read_b64_tr_b16 v[236:237], v166
	ds_read_b64_tr_b16 v[238:239], v166 offset:2304
	ds_read_b64_tr_b16 v[240:241], v166 offset:32
	ds_read_b64_tr_b16 v[242:243], v166 offset:2336
	ds_read_b64_tr_b16 v[244:245], v166 offset:64
	ds_read_b64_tr_b16 v[246:247], v166 offset:2368
	ds_read_b64_tr_b16 v[248:249], v166 offset:96
	ds_read_b64_tr_b16 v[250:251], v166 offset:2400
	s_waitcnt lgkmcnt(0)
	ds_write_b128 v165, v[96:99]
	ds_write_b128 v165, v[100:103] offset:1152
	ds_write_b128 v165, v[104:107] offset:2304
	ds_write_b128 v165, v[108:111] offset:3456
	v_mfma_f32_16x16x32_bf16 v[204:207], v[236:239], v[116:119], v[204:207]
	v_mfma_f32_16x16x32_bf16 v[208:211], v[240:243], v[116:119], v[208:211]
	v_mfma_f32_16x16x32_bf16 v[212:215], v[244:247], v[116:119], v[212:215]
	v_mfma_f32_16x16x32_bf16 v[216:219], v[248:251], v[116:119], v[216:219]
	s_waitcnt lgkmcnt(0)
	ds_read_b64_tr_b16 v[236:237], v166
	ds_read_b64_tr_b16 v[238:239], v166 offset:2304
	ds_read_b64_tr_b16 v[240:241], v166 offset:32
	ds_read_b64_tr_b16 v[242:243], v166 offset:2336
	ds_read_b64_tr_b16 v[244:245], v166 offset:64
	ds_read_b64_tr_b16 v[246:247], v166 offset:2368
	ds_read_b64_tr_b16 v[248:249], v166 offset:96
	ds_read_b64_tr_b16 v[250:251], v166 offset:2400
	s_waitcnt lgkmcnt(0)
	s_waitcnt vmcnt(10)
	ds_write_b128 v165, v[16:19]
	ds_write_b128 v165, v[20:23] offset:1152
	ds_write_b128 v165, v[24:27] offset:2304
	ds_write_b128 v165, v[28:31] offset:3456
	v_mfma_f32_16x16x32_bf16 v[204:207], v[236:239], v[120:123], v[204:207]
	v_mfma_f32_16x16x32_bf16 v[208:211], v[240:243], v[120:123], v[208:211]
	v_mfma_f32_16x16x32_bf16 v[212:215], v[244:247], v[120:123], v[212:215]
	v_mfma_f32_16x16x32_bf16 v[216:219], v[248:251], v[120:123], v[216:219]
	s_waitcnt lgkmcnt(0)
	ds_read_b64_tr_b16 v[236:237], v166
	ds_read_b64_tr_b16 v[238:239], v166 offset:2304
	ds_read_b64_tr_b16 v[240:241], v166 offset:32
	ds_read_b64_tr_b16 v[242:243], v166 offset:2336
	ds_read_b64_tr_b16 v[244:245], v166 offset:64
	ds_read_b64_tr_b16 v[246:247], v166 offset:2368
	ds_read_b64_tr_b16 v[248:249], v166 offset:96
	ds_read_b64_tr_b16 v[250:251], v166 offset:2400
	s_waitcnt lgkmcnt(0)
	s_mul_i32 s2, s0, 48
	s_add_i32 s2, s2, s15
	s_add_i32 s2, s2, -32
	v_add_u32_e32 v138, s2, v164
	v_and_b32_e32 v139, 3, v138
	v_lshlrev_b32_e32 v139, s13, v139
	v_bfe_u32 v140, v138, 2, 2
	v_add_u32_e32 v139, v139, v140
	v_lshl_add_u32 v139, v139, 7, v162
	v_ashrrev_i32_e32 v138, 4, v138
	v_med3_i32 v138, v138, 0, s14
	v_lshl_add_u32 v138, v138, 9, v139
	global_load_dwordx4 v[16:19], v138, s[20:21]
	s_mul_i32 s2, s0, 48
	s_add_i32 s2, s2, s15
	s_add_i32 s2, s2, -24
	v_add_u32_e32 v138, s2, v164
	v_and_b32_e32 v139, 3, v138
	v_lshlrev_b32_e32 v139, s13, v139
	v_bfe_u32 v140, v138, 2, 2
	v_add_u32_e32 v139, v139, v140
	v_lshl_add_u32 v139, v139, 7, v162
	v_ashrrev_i32_e32 v138, 4, v138
	v_med3_i32 v138, v138, 0, s14
	v_lshl_add_u32 v138, v138, 9, v139
	global_load_dwordx4 v[20:23], v138, s[20:21]
	s_mul_i32 s2, s0, 48
	s_add_i32 s2, s2, s15
	s_add_i32 s2, s2, -64
	v_add_u32_e32 v138, s2, v164
	v_and_b32_e32 v139, 3, v138
	v_lshlrev_b32_e32 v139, s13, v139
	v_bfe_u32 v140, v138, 2, 2
	v_add_u32_e32 v139, v139, v140
	v_lshl_add_u32 v139, v139, 7, v162
	v_ashrrev_i32_e32 v138, 4, v138
	v_med3_i32 v138, v138, 0, s14
	v_lshl_add_u32 v138, v138, 9, v139
	global_load_dwordx4 v[24:27], v138, s[22:23]
	s_mul_i32 s2, s0, 48
	s_add_i32 s2, s2, s15
	s_add_i32 s2, s2, -56
	v_add_u32_e32 v138, s2, v164
	v_and_b32_e32 v139, 3, v138
	v_lshlrev_b32_e32 v139, s13, v139
	v_bfe_u32 v140, v138, 2, 2
	v_add_u32_e32 v139, v139, v140
	v_lshl_add_u32 v139, v139, 7, v162
	v_ashrrev_i32_e32 v138, 4, v138
	v_med3_i32 v138, v138, 0, s14
	v_lshl_add_u32 v138, v138, 9, v139
	global_load_dwordx4 v[28:31], v138, s[22:23]
	s_waitcnt vmcnt(12)
	ds_write_b128 v165, v[32:35]
	ds_write_b128 v165, v[36:39] offset:1152
	v_mfma_f32_16x16x32_bf16 v[204:207], v[236:239], v[124:127], v[204:207]
	v_mfma_f32_16x16x32_bf16 v[208:211], v[240:243], v[124:127], v[208:211]
	v_mfma_f32_16x16x32_bf16 v[212:215], v[244:247], v[124:127], v[212:215]
	v_mfma_f32_16x16x32_bf16 v[216:219], v[248:251], v[124:127], v[216:219]
	s_waitcnt lgkmcnt(0)
	ds_read_b64_tr_b16 v[236:237], v166
	ds_read_b64_tr_b16 v[238:239], v166 offset:2304
	ds_read_b64_tr_b16 v[240:241], v166 offset:32
	ds_read_b64_tr_b16 v[242:243], v166 offset:2336
	ds_read_b64_tr_b16 v[244:245], v166 offset:64
	ds_read_b64_tr_b16 v[246:247], v166 offset:2368
	ds_read_b64_tr_b16 v[248:249], v166 offset:96
	ds_read_b64_tr_b16 v[250:251], v166 offset:2400
	s_waitcnt lgkmcnt(0)
	s_mul_i32 s2, s0, 48
	s_add_i32 s2, s2, s15
	s_add_i32 s2, s2, -48
	v_add_u32_e32 v138, s2, v164
	v_and_b32_e32 v139, 3, v138
	v_lshlrev_b32_e32 v139, s13, v139
	v_bfe_u32 v140, v138, 2, 2
	v_add_u32_e32 v139, v139, v140
	v_lshl_add_u32 v139, v139, 7, v162
	v_ashrrev_i32_e32 v138, 4, v138
	v_med3_i32 v138, v138, 0, s14
	v_lshl_add_u32 v138, v138, 9, v139
	global_load_dwordx4 v[32:35], v138, s[22:23]
	s_mul_i32 s2, s0, 48
	s_add_i32 s2, s2, s15
	s_add_i32 s2, s2, -40
	v_add_u32_e32 v138, s2, v164
	v_and_b32_e32 v139, 3, v138
	v_lshlrev_b32_e32 v139, s13, v139
	v_bfe_u32 v140, v138, 2, 2
	v_add_u32_e32 v139, v139, v140
	v_lshl_add_u32 v139, v139, 7, v162
	v_ashrrev_i32_e32 v138, 4, v138
	v_med3_i32 v138, v138, 0, s14
	v_lshl_add_u32 v138, v138, 9, v139
	global_load_dwordx4 v[36:39], v138, s[22:23]
	s_mul_i32 s2, s0, 48
	s_add_i32 s2, s2, s15
	s_add_i32 s2, s2, -32
	v_add_u32_e32 v138, s2, v164
	v_and_b32_e32 v139, 3, v138
	v_lshlrev_b32_e32 v139, s13, v139
	v_bfe_u32 v140, v138, 2, 2
	v_add_u32_e32 v139, v139, v140
	v_lshl_add_u32 v139, v139, 7, v162
	v_ashrrev_i32_e32 v138, 4, v138
	v_med3_i32 v138, v138, 0, s14
	v_lshl_add_u32 v138, v138, 9, v139
	global_load_dwordx4 v[40:43], v138, s[22:23]
	s_mul_i32 s2, s0, 48
	s_add_i32 s2, s2, s15
	s_add_i32 s2, s2, -24
	v_add_u32_e32 v138, s2, v164
	v_and_b32_e32 v139, 3, v138
	v_lshlrev_b32_e32 v139, s13, v139
	v_bfe_u32 v140, v138, 2, 2
	v_add_u32_e32 v139, v139, v140
	v_lshl_add_u32 v139, v139, 7, v162
	v_ashrrev_i32_e32 v138, 4, v138
	v_med3_i32 v138, v138, 0, s14
	v_lshl_add_u32 v138, v138, 9, v139
	global_load_dwordx4 v[44:47], v138, s[22:23]
	v_mfma_f32_16x16x32_bf16 v[204:207], v[236:239], v[128:131], v[204:207]
	v_mfma_f32_16x16x32_bf16 v[208:211], v[240:243], v[128:131], v[208:211]
	v_mfma_f32_16x16x32_bf16 v[212:215], v[244:247], v[128:131], v[212:215]
	v_mfma_f32_16x16x32_bf16 v[216:219], v[248:251], v[128:131], v[216:219]
	ds_read_b128 v[236:239], v173 offset:0
	ds_read_b128 v[240:243], v173 offset:64
	ds_read_b128 v[244:247], v173 offset:128
	ds_read_b128 v[248:251], v173 offset:192
	ds_read_b32 v142, v174 offset:0
	s_waitcnt lgkmcnt(0)
	v_add_f32_e32 v204, v236, v204
	v_add_f32_e32 v205, v237, v205
	v_add_f32_e32 v206, v238, v206
	v_add_f32_e32 v207, v239, v207
	v_add_f32_e32 v208, v240, v208
	v_add_f32_e32 v209, v241, v209
	v_add_f32_e32 v210, v242, v210
	v_add_f32_e32 v211, v243, v211
	v_add_f32_e32 v212, v244, v212
	v_add_f32_e32 v213, v245, v213
	v_add_f32_e32 v214, v246, v214
	v_add_f32_e32 v215, v247, v215
	v_add_f32_e32 v216, v248, v216
	v_add_f32_e32 v217, v249, v217
	v_add_f32_e32 v218, v250, v218
	v_add_f32_e32 v219, v251, v219
	v_add_f32_e32 v132, v142, v132
	ds_write_b128 v173, v[204:207] offset:0
	ds_write_b128 v173, v[208:211] offset:64
	ds_write_b128 v173, v[212:215] offset:128
	ds_write_b128 v173, v[216:219] offset:192
	ds_write_b32 v174, v132 offset:0
	s_waitcnt lgkmcnt(0)
	s_barrier
	ds_read_b128 v[204:207], v170
	ds_read_b128 v[208:211], v170 offset:16
	ds_read_b128 v[212:215], v170 offset:32
	ds_read_b128 v[216:219], v170 offset:48
	ds_read_b128 v[220:223], v170 offset:64
	ds_read_b128 v[224:227], v170 offset:80
	ds_read_b128 v[228:231], v170 offset:96
	ds_read_b128 v[232:235], v170 offset:112
	ds_read_b32 v142, v171
	s_lshl_b32 s2, s35, 11
	s_lshl_b32 s3, s36, 7
	s_add_u32 s2, s2, s3
	s_add_u32 s90, s6, s2
	s_addc_u32 s91, s7, 0
	s_waitcnt lgkmcnt(0)
	v_div_scale_f32 v143, s[30:31], v142, v142, 1.0
	v_rcp_f32_e32 v147, v143
	v_div_scale_f32 v134, vcc, 1.0, v142, 1.0
	v_fma_f32 v135, -v143, v147, 1.0
	v_fmac_f32_e32 v147, v135, v147
	v_mul_f32_e32 v135, v134, v147
	v_fma_f32 v136, -v143, v135, v134
	v_fmac_f32_e32 v135, v136, v147
	v_fma_f32 v143, -v143, v135, v134
	v_div_fmas_f32 v143, v143, v147, v135
	v_div_fixup_f32 v142, v143, v142, 1.0
	v_mul_f32_e32 v204, v142, v204
	v_mul_f32_e32 v205, v142, v205
	v_mul_f32_e32 v206, v142, v206
	v_mul_f32_e32 v207, v142, v207
	v_mul_f32_e32 v208, v142, v208
	v_mul_f32_e32 v209, v142, v209
	v_mul_f32_e32 v210, v142, v210
	v_mul_f32_e32 v211, v142, v211
	v_mul_f32_e32 v212, v142, v212
	v_mul_f32_e32 v213, v142, v213
	v_mul_f32_e32 v214, v142, v214
	v_mul_f32_e32 v215, v142, v215
	v_mul_f32_e32 v216, v142, v216
	v_mul_f32_e32 v217, v142, v217
	v_mul_f32_e32 v218, v142, v218
	v_mul_f32_e32 v219, v142, v219
	v_mul_f32_e32 v220, v142, v220
	v_mul_f32_e32 v221, v142, v221
	v_mul_f32_e32 v222, v142, v222
	v_mul_f32_e32 v223, v142, v223
	v_mul_f32_e32 v224, v142, v224
	v_mul_f32_e32 v225, v142, v225
	v_mul_f32_e32 v226, v142, v226
	v_mul_f32_e32 v227, v142, v227
	v_mul_f32_e32 v228, v142, v228
	v_mul_f32_e32 v229, v142, v229
	v_mul_f32_e32 v230, v142, v230
	v_mul_f32_e32 v231, v142, v231
	v_mul_f32_e32 v232, v142, v232
	v_mul_f32_e32 v233, v142, v233
	v_mul_f32_e32 v234, v142, v234
	v_mul_f32_e32 v235, v142, v235
	v_cvt_pk_bf16_f32 v112, v204, v205
	v_cvt_pk_bf16_f32 v113, v206, v207
	v_cvt_pk_bf16_f32 v114, v208, v209
	v_cvt_pk_bf16_f32 v115, v210, v211
	v_cvt_pk_bf16_f32 v116, v212, v213
	v_cvt_pk_bf16_f32 v117, v214, v215
	v_cvt_pk_bf16_f32 v118, v216, v217
	v_cvt_pk_bf16_f32 v119, v218, v219
	v_cvt_pk_bf16_f32 v120, v220, v221
	v_cvt_pk_bf16_f32 v121, v222, v223
	v_cvt_pk_bf16_f32 v122, v224, v225
	v_cvt_pk_bf16_f32 v123, v226, v227
	v_cvt_pk_bf16_f32 v124, v228, v229
	v_cvt_pk_bf16_f32 v125, v230, v231
	v_cvt_pk_bf16_f32 v126, v232, v233
	v_cvt_pk_bf16_f32 v127, v234, v235
	global_store_dwordx4 v172, v[112:115], s[90:91] nt
	global_store_dwordx4 v172, v[116:119], s[90:91] offset:16 nt
	global_store_dwordx4 v172, v[120:123], s[90:91] offset:32 nt
	global_store_dwordx4 v172, v[124:127], s[90:91] offset:48 nt
	s_barrier
	s_cmp_eq_u32 s37, 0
	s_cbranch_scc1 .Latt_unit
	s_waitcnt vmcnt(0)
	s_branch .LBB0_365
